# EpiWin: z stores of the silu(g) and gelu(g_lru) column tiles (read again only in M3) write-through
# speedup vs baseline: 1.0022x; 1.0022x over previous
; __device__ __forceinline__ unsigned pk2(float lo, float hi) { return pg8::cvt_pk_bf16(lo, hi); }
; __device__ __forceinline__ float siluf_(float x) { return x * sigmoidf_(x); }
; __device__ __forceinline__ float geluf_(float x) { const float z = 1.5957691216057308f * (x + 0.044715f * x * x * x); return x * sigmoidf_(z); }
;     __device__ __forceinline__ void operator()(const f32x4 (&acc)[2][2][4][2], const pg8::Unit& u, int wr, int wc, int fr, int fq) const {
;     ...
;             const int act = (pn == 7 || pn == 8) ? 1 : (pn == 10 ? 2 : 0);
; #pragma unroll
;             for (int ai = 0; ai < 2; ++ai)
; #pragma unroll
;                 for (int m = 0; m < 4; ++m) {
;                     const int row = row0 + ai * 128 + m * 16; const float r = rs[ai * 4 + m];
; #pragma unroll
;                     for (int bj = 0; bj < 2; ++bj) {
;                         float v[8];
; #pragma unroll
;                         for (int n = 0; n < 2; ++n)
; #pragma unroll
;                             for (int j = 0; j < 4; ++j) { float t = acc[ai][bj][m][n][j] * r; if (act == 1) t = siluf_(t); else if (act == 2) t = geluf_(t); v[n * 4 + j] = t; }
;                         u32x4 w; w.x = pk2(v[0], v[1]); w.y = pk2(v[2], v[3]); w.z = pk2(v[4], v[5]); w.w = pk2(v[6], v[7]);
;                         *(u32x4*)(Z + (size_t)row * IW + pn * 256 + bj * 128 + wc * 32 + 8 * fq) = w;
;                     }
;                 }
.Lwin_act_silu:
	v_pk_mul_f32 v[124:125], v[124:125], v[202:203] op_sel_hi:[1,0]
	v_pk_mul_f32 v[126:127], v[126:127], v[202:203] op_sel_hi:[1,0]
	v_pk_mul_f32 v[120:121], v[120:121], v[202:203] op_sel_hi:[1,0]
	v_pk_mul_f32 v[122:123], v[122:123], v[202:203] op_sel_hi:[1,0]
	v_pk_mul_f32 v[116:117], v[116:117], v[202:203] op_sel_hi:[1,0]
	v_pk_mul_f32 v[118:119], v[118:119], v[202:203] op_sel_hi:[1,0]
	v_pk_mul_f32 v[112:113], v[112:113], v[202:203] op_sel_hi:[1,0]
	v_pk_mul_f32 v[114:115], v[114:115], v[202:203] op_sel_hi:[1,0]
	v_pk_mul_f32 v[218:219], v[124:125], v[132:133] op_sel_hi:[1,0]
	v_pk_mul_f32 v[220:221], v[126:127], v[132:133] op_sel_hi:[1,0]
	v_pk_mul_f32 v[222:223], v[120:121], v[132:133] op_sel_hi:[1,0]
	v_pk_mul_f32 v[224:225], v[122:123], v[132:133] op_sel_hi:[1,0]
	v_pk_mul_f32 v[226:227], v[116:117], v[132:133] op_sel_hi:[1,0]
	v_pk_mul_f32 v[228:229], v[118:119], v[132:133] op_sel_hi:[1,0]
	v_pk_mul_f32 v[230:231], v[112:113], v[132:133] op_sel_hi:[1,0]
	v_pk_mul_f32 v[232:233], v[114:115], v[132:133] op_sel_hi:[1,0]
	v_exp_f32_e32 v218, v218
	v_exp_f32_e32 v219, v219
	v_exp_f32_e32 v220, v220
	v_exp_f32_e32 v221, v221
	v_exp_f32_e32 v222, v222
	v_exp_f32_e32 v223, v223
	v_exp_f32_e32 v224, v224
	v_exp_f32_e32 v225, v225
	v_exp_f32_e32 v226, v226
	v_exp_f32_e32 v227, v227
	v_exp_f32_e32 v228, v228
	v_exp_f32_e32 v229, v229
	v_exp_f32_e32 v230, v230
	v_exp_f32_e32 v231, v231
	v_exp_f32_e32 v232, v232
	v_exp_f32_e32 v233, v233
	v_pk_add_f32 v[218:219], v[218:219], v[128:129]
	v_pk_add_f32 v[220:221], v[220:221], v[128:129]
	v_pk_add_f32 v[222:223], v[222:223], v[128:129]
	v_pk_add_f32 v[224:225], v[224:225], v[128:129]
	v_pk_add_f32 v[226:227], v[226:227], v[128:129]
	v_pk_add_f32 v[228:229], v[228:229], v[128:129]
	v_pk_add_f32 v[230:231], v[230:231], v[128:129]
	v_pk_add_f32 v[232:233], v[232:233], v[128:129]
	v_rcp_f32_e32 v218, v218
	v_rcp_f32_e32 v219, v219
	v_rcp_f32_e32 v220, v220
	v_rcp_f32_e32 v221, v221
	v_rcp_f32_e32 v222, v222
	v_rcp_f32_e32 v223, v223
	v_rcp_f32_e32 v224, v224
	v_rcp_f32_e32 v225, v225
	v_rcp_f32_e32 v226, v226
	v_rcp_f32_e32 v227, v227
	v_rcp_f32_e32 v228, v228
	v_rcp_f32_e32 v229, v229
	v_rcp_f32_e32 v230, v230
	v_rcp_f32_e32 v231, v231
	v_rcp_f32_e32 v232, v232
	v_rcp_f32_e32 v233, v233
	v_pk_mul_f32 v[124:125], v[124:125], v[218:219]
	v_pk_mul_f32 v[126:127], v[126:127], v[220:221]
	v_pk_mul_f32 v[120:121], v[120:121], v[222:223]
	v_pk_mul_f32 v[122:123], v[122:123], v[224:225]
	v_pk_mul_f32 v[116:117], v[116:117], v[226:227]
	v_pk_mul_f32 v[118:119], v[118:119], v[228:229]
	v_pk_mul_f32 v[112:113], v[112:113], v[230:231]
	v_pk_mul_f32 v[114:115], v[114:115], v[232:233]
	v_cvt_pk_bf16_f32 v124, v124, v125
	v_cvt_pk_bf16_f32 v125, v126, v127
	v_cvt_pk_bf16_f32 v126, v120, v121
	v_cvt_pk_bf16_f32 v127, v122, v123
	v_cvt_pk_bf16_f32 v116, v116, v117
	v_cvt_pk_bf16_f32 v117, v118, v119
	v_cvt_pk_bf16_f32 v118, v112, v113
	v_cvt_pk_bf16_f32 v119, v114, v115
	v_mov_b32_e32 v140, v139
	global_store_dwordx4 v140, v[124:127], s[8:9] sc1
	v_add_u32_e32 v141, 0x100, v139
	global_store_dwordx4 v141, v[116:119], s[8:9] sc1
	v_pk_mul_f32 v[108:109], v[108:109], v[204:205] op_sel_hi:[1,0]
	v_pk_mul_f32 v[110:111], v[110:111], v[204:205] op_sel_hi:[1,0]
	v_pk_mul_f32 v[104:105], v[104:105], v[204:205] op_sel_hi:[1,0]
	v_pk_mul_f32 v[106:107], v[106:107], v[204:205] op_sel_hi:[1,0]
	v_pk_mul_f32 v[100:101], v[100:101], v[204:205] op_sel_hi:[1,0]
	v_pk_mul_f32 v[102:103], v[102:103], v[204:205] op_sel_hi:[1,0]
	v_pk_mul_f32 v[96:97], v[96:97], v[204:205] op_sel_hi:[1,0]
	v_pk_mul_f32 v[98:99], v[98:99], v[204:205] op_sel_hi:[1,0]
	v_pk_mul_f32 v[218:219], v[108:109], v[132:133] op_sel_hi:[1,0]
	v_pk_mul_f32 v[220:221], v[110:111], v[132:133] op_sel_hi:[1,0]
	v_pk_mul_f32 v[222:223], v[104:105], v[132:133] op_sel_hi:[1,0]
	v_pk_mul_f32 v[224:225], v[106:107], v[132:133] op_sel_hi:[1,0]
	v_pk_mul_f32 v[226:227], v[100:101], v[132:133] op_sel_hi:[1,0]
	v_pk_mul_f32 v[228:229], v[102:103], v[132:133] op_sel_hi:[1,0]
	v_pk_mul_f32 v[230:231], v[96:97], v[132:133] op_sel_hi:[1,0]
	v_pk_mul_f32 v[232:233], v[98:99], v[132:133] op_sel_hi:[1,0]
	v_exp_f32_e32 v218, v218
	v_exp_f32_e32 v219, v219
	v_exp_f32_e32 v220, v220
	v_exp_f32_e32 v221, v221
	v_exp_f32_e32 v222, v222
	v_exp_f32_e32 v223, v223
	v_exp_f32_e32 v224, v224
	v_exp_f32_e32 v225, v225
	v_exp_f32_e32 v226, v226
	v_exp_f32_e32 v227, v227
	v_exp_f32_e32 v228, v228
	v_exp_f32_e32 v229, v229
	v_exp_f32_e32 v230, v230
	v_exp_f32_e32 v231, v231
	v_exp_f32_e32 v232, v232
	v_exp_f32_e32 v233, v233
	v_pk_add_f32 v[218:219], v[218:219], v[128:129]
	v_pk_add_f32 v[220:221], v[220:221], v[128:129]
	v_pk_add_f32 v[222:223], v[222:223], v[128:129]
	v_pk_add_f32 v[224:225], v[224:225], v[128:129]
	v_pk_add_f32 v[226:227], v[226:227], v[128:129]
	v_pk_add_f32 v[228:229], v[228:229], v[128:129]
	v_pk_add_f32 v[230:231], v[230:231], v[128:129]
	v_pk_add_f32 v[232:233], v[232:233], v[128:129]
	v_rcp_f32_e32 v218, v218
	v_rcp_f32_e32 v219, v219
	v_rcp_f32_e32 v220, v220
	v_rcp_f32_e32 v221, v221
	v_rcp_f32_e32 v222, v222
	v_rcp_f32_e32 v223, v223
	v_rcp_f32_e32 v224, v224
	v_rcp_f32_e32 v225, v225
	v_rcp_f32_e32 v226, v226
	v_rcp_f32_e32 v227, v227
	v_rcp_f32_e32 v228, v228
	v_rcp_f32_e32 v229, v229
	v_rcp_f32_e32 v230, v230
	v_rcp_f32_e32 v231, v231
	v_rcp_f32_e32 v232, v232
	v_rcp_f32_e32 v233, v233
	v_pk_mul_f32 v[108:109], v[108:109], v[218:219]
	v_pk_mul_f32 v[110:111], v[110:111], v[220:221]
	v_pk_mul_f32 v[104:105], v[104:105], v[222:223]
	v_pk_mul_f32 v[106:107], v[106:107], v[224:225]
	v_pk_mul_f32 v[100:101], v[100:101], v[226:227]
; __device__ __forceinline__ unsigned pk2(float lo, float hi) { return pg8::cvt_pk_bf16(lo, hi); }
; __device__ __forceinline__ float siluf_(float x) { return x * sigmoidf_(x); }
; __device__ __forceinline__ float geluf_(float x) { const float z = 1.5957691216057308f * (x + 0.044715f * x * x * x); return x * sigmoidf_(z); }
;     __device__ __forceinline__ void operator()(const f32x4 (&acc)[2][2][4][2], const pg8::Unit& u, int wr, int wc, int fr, int fq) const {
;     ...
;             const int act = (pn == 7 || pn == 8) ? 1 : (pn == 10 ? 2 : 0);
; #pragma unroll
;             for (int ai = 0; ai < 2; ++ai)
; #pragma unroll
;                 for (int m = 0; m < 4; ++m) {
;                     const int row = row0 + ai * 128 + m * 16; const float r = rs[ai * 4 + m];
; #pragma unroll
;                     for (int bj = 0; bj < 2; ++bj) {
;                         float v[8];
; #pragma unroll
;                         for (int n = 0; n < 2; ++n)
; #pragma unroll
;                             for (int j = 0; j < 4; ++j) { float t = acc[ai][bj][m][n][j] * r; if (act == 1) t = siluf_(t); else if (act == 2) t = geluf_(t); v[n * 4 + j] = t; }
;                         u32x4 w; w.x = pk2(v[0], v[1]); w.y = pk2(v[2], v[3]); w.z = pk2(v[4], v[5]); w.w = pk2(v[6], v[7]);
;                         *(u32x4*)(Z + (size_t)row * IW + pn * 256 + bj * 128 + wc * 32 + 8 * fq) = w;
;                     }
;                 }
	v_pk_mul_f32 v[102:103], v[102:103], v[228:229]
	v_pk_mul_f32 v[96:97], v[96:97], v[230:231]
	v_pk_mul_f32 v[98:99], v[98:99], v[232:233]
	v_cvt_pk_bf16_f32 v108, v108, v109
	v_cvt_pk_bf16_f32 v109, v110, v111
	v_cvt_pk_bf16_f32 v110, v104, v105
	v_cvt_pk_bf16_f32 v111, v106, v107
	v_cvt_pk_bf16_f32 v100, v100, v101
	v_cvt_pk_bf16_f32 v101, v102, v103
	v_cvt_pk_bf16_f32 v102, v96, v97
	v_cvt_pk_bf16_f32 v103, v98, v99
	v_add_u32_e32 v140, 0x16000, v139
	global_store_dwordx4 v140, v[108:111], s[8:9] sc1
	v_add_u32_e32 v141, 0x16100, v139
	global_store_dwordx4 v141, v[100:103], s[8:9] sc1
	v_pk_mul_f32 v[92:93], v[92:93], v[206:207] op_sel_hi:[1,0]
	v_pk_mul_f32 v[94:95], v[94:95], v[206:207] op_sel_hi:[1,0]
	v_pk_mul_f32 v[88:89], v[88:89], v[206:207] op_sel_hi:[1,0]
	v_pk_mul_f32 v[90:91], v[90:91], v[206:207] op_sel_hi:[1,0]
	v_pk_mul_f32 v[84:85], v[84:85], v[206:207] op_sel_hi:[1,0]
	v_pk_mul_f32 v[86:87], v[86:87], v[206:207] op_sel_hi:[1,0]
	v_pk_mul_f32 v[80:81], v[80:81], v[206:207] op_sel_hi:[1,0]
	v_pk_mul_f32 v[82:83], v[82:83], v[206:207] op_sel_hi:[1,0]
	v_pk_mul_f32 v[218:219], v[92:93], v[132:133] op_sel_hi:[1,0]
	v_pk_mul_f32 v[220:221], v[94:95], v[132:133] op_sel_hi:[1,0]
	v_pk_mul_f32 v[222:223], v[88:89], v[132:133] op_sel_hi:[1,0]
	v_pk_mul_f32 v[224:225], v[90:91], v[132:133] op_sel_hi:[1,0]
	v_pk_mul_f32 v[226:227], v[84:85], v[132:133] op_sel_hi:[1,0]
	v_pk_mul_f32 v[228:229], v[86:87], v[132:133] op_sel_hi:[1,0]
	v_pk_mul_f32 v[230:231], v[80:81], v[132:133] op_sel_hi:[1,0]
	v_pk_mul_f32 v[232:233], v[82:83], v[132:133] op_sel_hi:[1,0]
	v_exp_f32_e32 v218, v218
	v_exp_f32_e32 v219, v219
	v_exp_f32_e32 v220, v220
	v_exp_f32_e32 v221, v221
	v_exp_f32_e32 v222, v222
	v_exp_f32_e32 v223, v223
	v_exp_f32_e32 v224, v224
	v_exp_f32_e32 v225, v225
	v_exp_f32_e32 v226, v226
	v_exp_f32_e32 v227, v227
	v_exp_f32_e32 v228, v228
	v_exp_f32_e32 v229, v229
	v_exp_f32_e32 v230, v230
	v_exp_f32_e32 v231, v231
	v_exp_f32_e32 v232, v232
	v_exp_f32_e32 v233, v233
	v_pk_add_f32 v[218:219], v[218:219], v[128:129]
	v_pk_add_f32 v[220:221], v[220:221], v[128:129]
	v_pk_add_f32 v[222:223], v[222:223], v[128:129]
	v_pk_add_f32 v[224:225], v[224:225], v[128:129]
	v_pk_add_f32 v[226:227], v[226:227], v[128:129]
	v_pk_add_f32 v[228:229], v[228:229], v[128:129]
	v_pk_add_f32 v[230:231], v[230:231], v[128:129]
	v_pk_add_f32 v[232:233], v[232:233], v[128:129]
	v_rcp_f32_e32 v218, v218
	v_rcp_f32_e32 v219, v219
	v_rcp_f32_e32 v220, v220
	v_rcp_f32_e32 v221, v221
	v_rcp_f32_e32 v222, v222
	v_rcp_f32_e32 v223, v223
	v_rcp_f32_e32 v224, v224
	v_rcp_f32_e32 v225, v225
	v_rcp_f32_e32 v226, v226
	v_rcp_f32_e32 v227, v227
	v_rcp_f32_e32 v228, v228
	v_rcp_f32_e32 v229, v229
	v_rcp_f32_e32 v230, v230
	v_rcp_f32_e32 v231, v231
	v_rcp_f32_e32 v232, v232
	v_rcp_f32_e32 v233, v233
	v_pk_mul_f32 v[92:93], v[92:93], v[218:219]
	v_pk_mul_f32 v[94:95], v[94:95], v[220:221]
	v_pk_mul_f32 v[88:89], v[88:89], v[222:223]
	v_pk_mul_f32 v[90:91], v[90:91], v[224:225]
	v_pk_mul_f32 v[84:85], v[84:85], v[226:227]
	v_pk_mul_f32 v[86:87], v[86:87], v[228:229]
	v_pk_mul_f32 v[80:81], v[80:81], v[230:231]
	v_pk_mul_f32 v[82:83], v[82:83], v[232:233]
	v_cvt_pk_bf16_f32 v92, v92, v93
	v_cvt_pk_bf16_f32 v93, v94, v95
	v_cvt_pk_bf16_f32 v94, v88, v89
	v_cvt_pk_bf16_f32 v95, v90, v91
	v_cvt_pk_bf16_f32 v84, v84, v85
	v_cvt_pk_bf16_f32 v85, v86, v87
	v_cvt_pk_bf16_f32 v86, v80, v81
	v_cvt_pk_bf16_f32 v87, v82, v83
	v_add_u32_e32 v140, 0x2c000, v139
	global_store_dwordx4 v140, v[92:95], s[8:9] sc1
	v_add_u32_e32 v141, 0x2c100, v139
	global_store_dwordx4 v141, v[84:87], s[8:9] sc1
	v_pk_mul_f32 v[76:77], v[76:77], v[208:209] op_sel_hi:[1,0]
	v_pk_mul_f32 v[78:79], v[78:79], v[208:209] op_sel_hi:[1,0]
	v_pk_mul_f32 v[72:73], v[72:73], v[208:209] op_sel_hi:[1,0]
	v_pk_mul_f32 v[74:75], v[74:75], v[208:209] op_sel_hi:[1,0]
	v_pk_mul_f32 v[68:69], v[68:69], v[208:209] op_sel_hi:[1,0]
	v_pk_mul_f32 v[70:71], v[70:71], v[208:209] op_sel_hi:[1,0]
	v_pk_mul_f32 v[64:65], v[64:65], v[208:209] op_sel_hi:[1,0]
	v_pk_mul_f32 v[66:67], v[66:67], v[208:209] op_sel_hi:[1,0]
	v_pk_mul_f32 v[218:219], v[76:77], v[132:133] op_sel_hi:[1,0]
	v_pk_mul_f32 v[220:221], v[78:79], v[132:133] op_sel_hi:[1,0]
	v_pk_mul_f32 v[222:223], v[72:73], v[132:133] op_sel_hi:[1,0]
	v_pk_mul_f32 v[224:225], v[74:75], v[132:133] op_sel_hi:[1,0]
	v_pk_mul_f32 v[226:227], v[68:69], v[132:133] op_sel_hi:[1,0]
	v_pk_mul_f32 v[228:229], v[70:71], v[132:133] op_sel_hi:[1,0]
	v_pk_mul_f32 v[230:231], v[64:65], v[132:133] op_sel_hi:[1,0]
	v_pk_mul_f32 v[232:233], v[66:67], v[132:133] op_sel_hi:[1,0]
	v_exp_f32_e32 v218, v218
	v_exp_f32_e32 v219, v219
	v_exp_f32_e32 v220, v220
	v_exp_f32_e32 v221, v221
	v_exp_f32_e32 v222, v222
	v_exp_f32_e32 v223, v223
	v_exp_f32_e32 v224, v224
	v_exp_f32_e32 v225, v225
	v_exp_f32_e32 v226, v226
	v_exp_f32_e32 v227, v227
	v_exp_f32_e32 v228, v228
	v_exp_f32_e32 v229, v229
	v_exp_f32_e32 v230, v230
	v_exp_f32_e32 v231, v231
	v_exp_f32_e32 v232, v232
	v_exp_f32_e32 v233, v233
	v_pk_add_f32 v[218:219], v[218:219], v[128:129]
	v_pk_add_f32 v[220:221], v[220:221], v[128:129]
	v_pk_add_f32 v[222:223], v[222:223], v[128:129]
	v_pk_add_f32 v[224:225], v[224:225], v[128:129]
	v_pk_add_f32 v[226:227], v[226:227], v[128:129]
	v_pk_add_f32 v[228:229], v[228:229], v[128:129]
	v_pk_add_f32 v[230:231], v[230:231], v[128:129]
	v_pk_add_f32 v[232:233], v[232:233], v[128:129]
	v_rcp_f32_e32 v218, v218
	v_rcp_f32_e32 v219, v219
	v_rcp_f32_e32 v220, v220
	v_rcp_f32_e32 v221, v221
	v_rcp_f32_e32 v222, v222
	v_rcp_f32_e32 v223, v223
	v_rcp_f32_e32 v224, v224
	v_rcp_f32_e32 v225, v225
	v_rcp_f32_e32 v226, v226
; __device__ __forceinline__ unsigned pk2(float lo, float hi) { return pg8::cvt_pk_bf16(lo, hi); }
; __device__ __forceinline__ float siluf_(float x) { return x * sigmoidf_(x); }
; __device__ __forceinline__ float geluf_(float x) { const float z = 1.5957691216057308f * (x + 0.044715f * x * x * x); return x * sigmoidf_(z); }
;     __device__ __forceinline__ void operator()(const f32x4 (&acc)[2][2][4][2], const pg8::Unit& u, int wr, int wc, int fr, int fq) const {
;     ...
;             const int act = (pn == 7 || pn == 8) ? 1 : (pn == 10 ? 2 : 0);
; #pragma unroll
;             for (int ai = 0; ai < 2; ++ai)
; #pragma unroll
;                 for (int m = 0; m < 4; ++m) {
;                     const int row = row0 + ai * 128 + m * 16; const float r = rs[ai * 4 + m];
; #pragma unroll
;                     for (int bj = 0; bj < 2; ++bj) {
;                         float v[8];
; #pragma unroll
;                         for (int n = 0; n < 2; ++n)
; #pragma unroll
;                             for (int j = 0; j < 4; ++j) { float t = acc[ai][bj][m][n][j] * r; if (act == 1) t = siluf_(t); else if (act == 2) t = geluf_(t); v[n * 4 + j] = t; }
;                         u32x4 w; w.x = pk2(v[0], v[1]); w.y = pk2(v[2], v[3]); w.z = pk2(v[4], v[5]); w.w = pk2(v[6], v[7]);
;                         *(u32x4*)(Z + (size_t)row * IW + pn * 256 + bj * 128 + wc * 32 + 8 * fq) = w;
;                     }
;                 }
	v_rcp_f32_e32 v227, v227
	v_rcp_f32_e32 v228, v228
	v_rcp_f32_e32 v229, v229
	v_rcp_f32_e32 v230, v230
	v_rcp_f32_e32 v231, v231
	v_rcp_f32_e32 v232, v232
	v_rcp_f32_e32 v233, v233
	v_pk_mul_f32 v[76:77], v[76:77], v[218:219]
	v_pk_mul_f32 v[78:79], v[78:79], v[220:221]
	v_pk_mul_f32 v[72:73], v[72:73], v[222:223]
	v_pk_mul_f32 v[74:75], v[74:75], v[224:225]
	v_pk_mul_f32 v[68:69], v[68:69], v[226:227]
	v_pk_mul_f32 v[70:71], v[70:71], v[228:229]
	v_pk_mul_f32 v[64:65], v[64:65], v[230:231]
	v_pk_mul_f32 v[66:67], v[66:67], v[232:233]
	v_cvt_pk_bf16_f32 v76, v76, v77
	v_cvt_pk_bf16_f32 v77, v78, v79
	v_cvt_pk_bf16_f32 v78, v72, v73
	v_cvt_pk_bf16_f32 v79, v74, v75
	v_cvt_pk_bf16_f32 v68, v68, v69
	v_cvt_pk_bf16_f32 v69, v70, v71
	v_cvt_pk_bf16_f32 v70, v64, v65
	v_cvt_pk_bf16_f32 v71, v66, v67
	v_add_u32_e32 v140, 0x42000, v139
	global_store_dwordx4 v140, v[76:79], s[8:9] sc1
	v_add_u32_e32 v141, 0x42100, v139
	global_store_dwordx4 v141, v[68:71], s[8:9] sc1
	v_pk_mul_f32 v[60:61], v[60:61], v[210:211] op_sel_hi:[1,0]
	v_pk_mul_f32 v[62:63], v[62:63], v[210:211] op_sel_hi:[1,0]
	v_pk_mul_f32 v[56:57], v[56:57], v[210:211] op_sel_hi:[1,0]
	v_pk_mul_f32 v[58:59], v[58:59], v[210:211] op_sel_hi:[1,0]
	v_pk_mul_f32 v[52:53], v[52:53], v[210:211] op_sel_hi:[1,0]
	v_pk_mul_f32 v[54:55], v[54:55], v[210:211] op_sel_hi:[1,0]
	v_pk_mul_f32 v[48:49], v[48:49], v[210:211] op_sel_hi:[1,0]
	v_pk_mul_f32 v[50:51], v[50:51], v[210:211] op_sel_hi:[1,0]
	v_pk_mul_f32 v[218:219], v[60:61], v[132:133] op_sel_hi:[1,0]
	v_pk_mul_f32 v[220:221], v[62:63], v[132:133] op_sel_hi:[1,0]
	v_pk_mul_f32 v[222:223], v[56:57], v[132:133] op_sel_hi:[1,0]
	v_pk_mul_f32 v[224:225], v[58:59], v[132:133] op_sel_hi:[1,0]
	v_pk_mul_f32 v[226:227], v[52:53], v[132:133] op_sel_hi:[1,0]
	v_pk_mul_f32 v[228:229], v[54:55], v[132:133] op_sel_hi:[1,0]
	v_pk_mul_f32 v[230:231], v[48:49], v[132:133] op_sel_hi:[1,0]
	v_pk_mul_f32 v[232:233], v[50:51], v[132:133] op_sel_hi:[1,0]
	v_exp_f32_e32 v218, v218
	v_exp_f32_e32 v219, v219
	v_exp_f32_e32 v220, v220
	v_exp_f32_e32 v221, v221
	v_exp_f32_e32 v222, v222
	v_exp_f32_e32 v223, v223
	v_exp_f32_e32 v224, v224
	v_exp_f32_e32 v225, v225
	v_exp_f32_e32 v226, v226
	v_exp_f32_e32 v227, v227
	v_exp_f32_e32 v228, v228
	v_exp_f32_e32 v229, v229
	v_exp_f32_e32 v230, v230
	v_exp_f32_e32 v231, v231
	v_exp_f32_e32 v232, v232
	v_exp_f32_e32 v233, v233
	v_pk_add_f32 v[218:219], v[218:219], v[128:129]
	v_pk_add_f32 v[220:221], v[220:221], v[128:129]
	v_pk_add_f32 v[222:223], v[222:223], v[128:129]
	v_pk_add_f32 v[224:225], v[224:225], v[128:129]
	v_pk_add_f32 v[226:227], v[226:227], v[128:129]
	v_pk_add_f32 v[228:229], v[228:229], v[128:129]
	v_pk_add_f32 v[230:231], v[230:231], v[128:129]
	v_pk_add_f32 v[232:233], v[232:233], v[128:129]
	v_rcp_f32_e32 v218, v218
	v_rcp_f32_e32 v219, v219
	v_rcp_f32_e32 v220, v220
	v_rcp_f32_e32 v221, v221
	v_rcp_f32_e32 v222, v222
	v_rcp_f32_e32 v223, v223
	v_rcp_f32_e32 v224, v224
	v_rcp_f32_e32 v225, v225
	v_rcp_f32_e32 v226, v226
	v_rcp_f32_e32 v227, v227
	v_rcp_f32_e32 v228, v228
	v_rcp_f32_e32 v229, v229
	v_rcp_f32_e32 v230, v230
	v_rcp_f32_e32 v231, v231
	v_rcp_f32_e32 v232, v232
	v_rcp_f32_e32 v233, v233
	v_pk_mul_f32 v[60:61], v[60:61], v[218:219]
	v_pk_mul_f32 v[62:63], v[62:63], v[220:221]
	v_pk_mul_f32 v[56:57], v[56:57], v[222:223]
	v_pk_mul_f32 v[58:59], v[58:59], v[224:225]
	v_pk_mul_f32 v[52:53], v[52:53], v[226:227]
	v_pk_mul_f32 v[54:55], v[54:55], v[228:229]
	v_pk_mul_f32 v[48:49], v[48:49], v[230:231]
	v_pk_mul_f32 v[50:51], v[50:51], v[232:233]
	v_cvt_pk_bf16_f32 v60, v60, v61
	v_cvt_pk_bf16_f32 v61, v62, v63
	v_cvt_pk_bf16_f32 v62, v56, v57
	v_cvt_pk_bf16_f32 v63, v58, v59
	v_cvt_pk_bf16_f32 v52, v52, v53
	v_cvt_pk_bf16_f32 v53, v54, v55
	v_cvt_pk_bf16_f32 v54, v48, v49
	v_cvt_pk_bf16_f32 v55, v50, v51
	v_add_u32_e32 v140, 0xb0000, v139
	global_store_dwordx4 v140, v[60:63], s[8:9] sc1
	v_add_u32_e32 v141, 0xb0100, v139
	global_store_dwordx4 v141, v[52:55], s[8:9] sc1
	v_pk_mul_f32 v[44:45], v[44:45], v[212:213] op_sel_hi:[1,0]
	v_pk_mul_f32 v[46:47], v[46:47], v[212:213] op_sel_hi:[1,0]
	v_pk_mul_f32 v[40:41], v[40:41], v[212:213] op_sel_hi:[1,0]
	v_pk_mul_f32 v[42:43], v[42:43], v[212:213] op_sel_hi:[1,0]
	v_pk_mul_f32 v[36:37], v[36:37], v[212:213] op_sel_hi:[1,0]
	v_pk_mul_f32 v[38:39], v[38:39], v[212:213] op_sel_hi:[1,0]
	v_pk_mul_f32 v[32:33], v[32:33], v[212:213] op_sel_hi:[1,0]
	v_pk_mul_f32 v[34:35], v[34:35], v[212:213] op_sel_hi:[1,0]
	v_pk_mul_f32 v[218:219], v[44:45], v[132:133] op_sel_hi:[1,0]
	v_pk_mul_f32 v[220:221], v[46:47], v[132:133] op_sel_hi:[1,0]
	v_pk_mul_f32 v[222:223], v[40:41], v[132:133] op_sel_hi:[1,0]
	v_pk_mul_f32 v[224:225], v[42:43], v[132:133] op_sel_hi:[1,0]
	v_pk_mul_f32 v[226:227], v[36:37], v[132:133] op_sel_hi:[1,0]
	v_pk_mul_f32 v[228:229], v[38:39], v[132:133] op_sel_hi:[1,0]
	v_pk_mul_f32 v[230:231], v[32:33], v[132:133] op_sel_hi:[1,0]
	v_pk_mul_f32 v[232:233], v[34:35], v[132:133] op_sel_hi:[1,0]
	v_exp_f32_e32 v218, v218
	v_exp_f32_e32 v219, v219
	v_exp_f32_e32 v220, v220
	v_exp_f32_e32 v221, v221
	v_exp_f32_e32 v222, v222
	v_exp_f32_e32 v223, v223
	v_exp_f32_e32 v224, v224
	v_exp_f32_e32 v225, v225
	v_exp_f32_e32 v226, v226
	v_exp_f32_e32 v227, v227
	v_exp_f32_e32 v228, v228
	v_exp_f32_e32 v229, v229
	v_exp_f32_e32 v230, v230
	v_exp_f32_e32 v231, v231
	v_exp_f32_e32 v232, v232
	v_exp_f32_e32 v233, v233
	v_pk_add_f32 v[218:219], v[218:219], v[128:129]
	v_pk_add_f32 v[220:221], v[220:221], v[128:129]
	v_pk_add_f32 v[222:223], v[222:223], v[128:129]
	v_pk_add_f32 v[224:225], v[224:225], v[128:129]
	v_pk_add_f32 v[226:227], v[226:227], v[128:129]
; __device__ __forceinline__ unsigned pk2(float lo, float hi) { return pg8::cvt_pk_bf16(lo, hi); }
; __device__ __forceinline__ float siluf_(float x) { return x * sigmoidf_(x); }
; __device__ __forceinline__ float geluf_(float x) { const float z = 1.5957691216057308f * (x + 0.044715f * x * x * x); return x * sigmoidf_(z); }
;     __device__ __forceinline__ void operator()(const f32x4 (&acc)[2][2][4][2], const pg8::Unit& u, int wr, int wc, int fr, int fq) const {
;     ...
;             const int act = (pn == 7 || pn == 8) ? 1 : (pn == 10 ? 2 : 0);
; #pragma unroll
;             for (int ai = 0; ai < 2; ++ai)
; #pragma unroll
;                 for (int m = 0; m < 4; ++m) {
;                     const int row = row0 + ai * 128 + m * 16; const float r = rs[ai * 4 + m];
; #pragma unroll
;                     for (int bj = 0; bj < 2; ++bj) {
;                         float v[8];
; #pragma unroll
;                         for (int n = 0; n < 2; ++n)
; #pragma unroll
;                             for (int j = 0; j < 4; ++j) { float t = acc[ai][bj][m][n][j] * r; if (act == 1) t = siluf_(t); else if (act == 2) t = geluf_(t); v[n * 4 + j] = t; }
;                         u32x4 w; w.x = pk2(v[0], v[1]); w.y = pk2(v[2], v[3]); w.z = pk2(v[4], v[5]); w.w = pk2(v[6], v[7]);
;                         *(u32x4*)(Z + (size_t)row * IW + pn * 256 + bj * 128 + wc * 32 + 8 * fq) = w;
;                     }
;                 }
	v_pk_add_f32 v[228:229], v[228:229], v[128:129]
	v_pk_add_f32 v[230:231], v[230:231], v[128:129]
	v_pk_add_f32 v[232:233], v[232:233], v[128:129]
	v_rcp_f32_e32 v218, v218
	v_rcp_f32_e32 v219, v219
	v_rcp_f32_e32 v220, v220
	v_rcp_f32_e32 v221, v221
	v_rcp_f32_e32 v222, v222
	v_rcp_f32_e32 v223, v223
	v_rcp_f32_e32 v224, v224
	v_rcp_f32_e32 v225, v225
	v_rcp_f32_e32 v226, v226
	v_rcp_f32_e32 v227, v227
	v_rcp_f32_e32 v228, v228
	v_rcp_f32_e32 v229, v229
	v_rcp_f32_e32 v230, v230
	v_rcp_f32_e32 v231, v231
	v_rcp_f32_e32 v232, v232
	v_rcp_f32_e32 v233, v233
	v_pk_mul_f32 v[44:45], v[44:45], v[218:219]
	v_pk_mul_f32 v[46:47], v[46:47], v[220:221]
	v_pk_mul_f32 v[40:41], v[40:41], v[222:223]
	v_pk_mul_f32 v[42:43], v[42:43], v[224:225]
	v_pk_mul_f32 v[36:37], v[36:37], v[226:227]
	v_pk_mul_f32 v[38:39], v[38:39], v[228:229]
	v_pk_mul_f32 v[32:33], v[32:33], v[230:231]
	v_pk_mul_f32 v[34:35], v[34:35], v[232:233]
	v_cvt_pk_bf16_f32 v44, v44, v45
	v_cvt_pk_bf16_f32 v45, v46, v47
	v_cvt_pk_bf16_f32 v46, v40, v41
	v_cvt_pk_bf16_f32 v47, v42, v43
	v_cvt_pk_bf16_f32 v36, v36, v37
	v_cvt_pk_bf16_f32 v37, v38, v39
	v_cvt_pk_bf16_f32 v38, v32, v33
	v_cvt_pk_bf16_f32 v39, v34, v35
	v_add_u32_e32 v140, 0xc6000, v139
	global_store_dwordx4 v140, v[44:47], s[8:9] sc1
	v_add_u32_e32 v141, 0xc6100, v139
	global_store_dwordx4 v141, v[36:39], s[8:9] sc1
	v_pk_mul_f32 v[28:29], v[28:29], v[214:215] op_sel_hi:[1,0]
	v_pk_mul_f32 v[30:31], v[30:31], v[214:215] op_sel_hi:[1,0]
	v_pk_mul_f32 v[24:25], v[24:25], v[214:215] op_sel_hi:[1,0]
	v_pk_mul_f32 v[26:27], v[26:27], v[214:215] op_sel_hi:[1,0]
	v_pk_mul_f32 v[20:21], v[20:21], v[214:215] op_sel_hi:[1,0]
	v_pk_mul_f32 v[22:23], v[22:23], v[214:215] op_sel_hi:[1,0]
	v_pk_mul_f32 v[16:17], v[16:17], v[214:215] op_sel_hi:[1,0]
	v_pk_mul_f32 v[18:19], v[18:19], v[214:215] op_sel_hi:[1,0]
	v_pk_mul_f32 v[218:219], v[28:29], v[132:133] op_sel_hi:[1,0]
	v_pk_mul_f32 v[220:221], v[30:31], v[132:133] op_sel_hi:[1,0]
	v_pk_mul_f32 v[222:223], v[24:25], v[132:133] op_sel_hi:[1,0]
	v_pk_mul_f32 v[224:225], v[26:27], v[132:133] op_sel_hi:[1,0]
	v_pk_mul_f32 v[226:227], v[20:21], v[132:133] op_sel_hi:[1,0]
	v_pk_mul_f32 v[228:229], v[22:23], v[132:133] op_sel_hi:[1,0]
	v_pk_mul_f32 v[230:231], v[16:17], v[132:133] op_sel_hi:[1,0]
	v_pk_mul_f32 v[232:233], v[18:19], v[132:133] op_sel_hi:[1,0]
	v_exp_f32_e32 v218, v218
	v_exp_f32_e32 v219, v219
	v_exp_f32_e32 v220, v220
	v_exp_f32_e32 v221, v221
	v_exp_f32_e32 v222, v222
	v_exp_f32_e32 v223, v223
	v_exp_f32_e32 v224, v224
	v_exp_f32_e32 v225, v225
	v_exp_f32_e32 v226, v226
	v_exp_f32_e32 v227, v227
	v_exp_f32_e32 v228, v228
	v_exp_f32_e32 v229, v229
	v_exp_f32_e32 v230, v230
	v_exp_f32_e32 v231, v231
	v_exp_f32_e32 v232, v232
	v_exp_f32_e32 v233, v233
	v_pk_add_f32 v[218:219], v[218:219], v[128:129]
	v_pk_add_f32 v[220:221], v[220:221], v[128:129]
	v_pk_add_f32 v[222:223], v[222:223], v[128:129]
	v_pk_add_f32 v[224:225], v[224:225], v[128:129]
	v_pk_add_f32 v[226:227], v[226:227], v[128:129]
	v_pk_add_f32 v[228:229], v[228:229], v[128:129]
	v_pk_add_f32 v[230:231], v[230:231], v[128:129]
	v_pk_add_f32 v[232:233], v[232:233], v[128:129]
	v_rcp_f32_e32 v218, v218
	v_rcp_f32_e32 v219, v219
	v_rcp_f32_e32 v220, v220
	v_rcp_f32_e32 v221, v221
	v_rcp_f32_e32 v222, v222
	v_rcp_f32_e32 v223, v223
	v_rcp_f32_e32 v224, v224
	v_rcp_f32_e32 v225, v225
	v_rcp_f32_e32 v226, v226
	v_rcp_f32_e32 v227, v227
	v_rcp_f32_e32 v228, v228
	v_rcp_f32_e32 v229, v229
	v_rcp_f32_e32 v230, v230
	v_rcp_f32_e32 v231, v231
	v_rcp_f32_e32 v232, v232
	v_rcp_f32_e32 v233, v233
	v_pk_mul_f32 v[28:29], v[28:29], v[218:219]
	v_pk_mul_f32 v[30:31], v[30:31], v[220:221]
	v_pk_mul_f32 v[24:25], v[24:25], v[222:223]
	v_pk_mul_f32 v[26:27], v[26:27], v[224:225]
	v_pk_mul_f32 v[20:21], v[20:21], v[226:227]
	v_pk_mul_f32 v[22:23], v[22:23], v[228:229]
	v_pk_mul_f32 v[16:17], v[16:17], v[230:231]
	v_pk_mul_f32 v[18:19], v[18:19], v[232:233]
	v_cvt_pk_bf16_f32 v28, v28, v29
	v_cvt_pk_bf16_f32 v29, v30, v31
	v_cvt_pk_bf16_f32 v30, v24, v25
	v_cvt_pk_bf16_f32 v31, v26, v27
	v_cvt_pk_bf16_f32 v20, v20, v21
	v_cvt_pk_bf16_f32 v21, v22, v23
	v_cvt_pk_bf16_f32 v22, v16, v17
	v_cvt_pk_bf16_f32 v23, v18, v19
	v_add_u32_e32 v140, 0xdc000, v139
	global_store_dwordx4 v140, v[28:31], s[8:9] sc1
	v_add_u32_e32 v141, 0xdc100, v139
	global_store_dwordx4 v141, v[20:23], s[8:9] sc1
	v_pk_mul_f32 v[12:13], v[12:13], v[216:217] op_sel_hi:[1,0]
	v_pk_mul_f32 v[14:15], v[14:15], v[216:217] op_sel_hi:[1,0]
	v_pk_mul_f32 v[8:9], v[8:9], v[216:217] op_sel_hi:[1,0]
	v_pk_mul_f32 v[10:11], v[10:11], v[216:217] op_sel_hi:[1,0]
	v_pk_mul_f32 v[4:5], v[4:5], v[216:217] op_sel_hi:[1,0]
	v_pk_mul_f32 v[6:7], v[6:7], v[216:217] op_sel_hi:[1,0]
	v_pk_mul_f32 v[0:1], v[0:1], v[216:217] op_sel_hi:[1,0]
	v_pk_mul_f32 v[2:3], v[2:3], v[216:217] op_sel_hi:[1,0]
	v_pk_mul_f32 v[218:219], v[12:13], v[132:133] op_sel_hi:[1,0]
	v_pk_mul_f32 v[220:221], v[14:15], v[132:133] op_sel_hi:[1,0]
	v_pk_mul_f32 v[222:223], v[8:9], v[132:133] op_sel_hi:[1,0]
	v_pk_mul_f32 v[224:225], v[10:11], v[132:133] op_sel_hi:[1,0]
	v_pk_mul_f32 v[226:227], v[4:5], v[132:133] op_sel_hi:[1,0]
	v_pk_mul_f32 v[228:229], v[6:7], v[132:133] op_sel_hi:[1,0]
	v_pk_mul_f32 v[230:231], v[0:1], v[132:133] op_sel_hi:[1,0]
	v_pk_mul_f32 v[232:233], v[2:3], v[132:133] op_sel_hi:[1,0]
	v_exp_f32_e32 v218, v218
	v_exp_f32_e32 v219, v219
	v_exp_f32_e32 v220, v220
	v_exp_f32_e32 v221, v221
	v_exp_f32_e32 v222, v222
	v_exp_f32_e32 v223, v223
	v_exp_f32_e32 v224, v224
	v_exp_f32_e32 v225, v225
	v_exp_f32_e32 v226, v226
	v_exp_f32_e32 v227, v227
	v_exp_f32_e32 v228, v228
	v_exp_f32_e32 v229, v229
; __device__ __forceinline__ unsigned pk2(float lo, float hi) { return pg8::cvt_pk_bf16(lo, hi); }
; __device__ __forceinline__ float siluf_(float x) { return x * sigmoidf_(x); }
; __device__ __forceinline__ float geluf_(float x) { const float z = 1.5957691216057308f * (x + 0.044715f * x * x * x); return x * sigmoidf_(z); }
;     __device__ __forceinline__ void operator()(const f32x4 (&acc)[2][2][4][2], const pg8::Unit& u, int wr, int wc, int fr, int fq) const {
;     ...
;             const int act = (pn == 7 || pn == 8) ? 1 : (pn == 10 ? 2 : 0);
; #pragma unroll
;             for (int ai = 0; ai < 2; ++ai)
; #pragma unroll
;                 for (int m = 0; m < 4; ++m) {
;                     const int row = row0 + ai * 128 + m * 16; const float r = rs[ai * 4 + m];
; #pragma unroll
;                     for (int bj = 0; bj < 2; ++bj) {
;                         float v[8];
; #pragma unroll
;                         for (int n = 0; n < 2; ++n)
; #pragma unroll
;                             for (int j = 0; j < 4; ++j) { float t = acc[ai][bj][m][n][j] * r; if (act == 1) t = siluf_(t); else if (act == 2) t = geluf_(t); v[n * 4 + j] = t; }
;                         u32x4 w; w.x = pk2(v[0], v[1]); w.y = pk2(v[2], v[3]); w.z = pk2(v[4], v[5]); w.w = pk2(v[6], v[7]);
;                         *(u32x4*)(Z + (size_t)row * IW + pn * 256 + bj * 128 + wc * 32 + 8 * fq) = w;
;                     }
;                 }
	v_exp_f32_e32 v230, v230
	v_exp_f32_e32 v231, v231
	v_exp_f32_e32 v232, v232
	v_exp_f32_e32 v233, v233
	v_pk_add_f32 v[218:219], v[218:219], v[128:129]
	v_pk_add_f32 v[220:221], v[220:221], v[128:129]
	v_pk_add_f32 v[222:223], v[222:223], v[128:129]
	v_pk_add_f32 v[224:225], v[224:225], v[128:129]
	v_pk_add_f32 v[226:227], v[226:227], v[128:129]
	v_pk_add_f32 v[228:229], v[228:229], v[128:129]
	v_pk_add_f32 v[230:231], v[230:231], v[128:129]
	v_pk_add_f32 v[232:233], v[232:233], v[128:129]
	v_rcp_f32_e32 v218, v218
	v_rcp_f32_e32 v219, v219
	v_rcp_f32_e32 v220, v220
	v_rcp_f32_e32 v221, v221
	v_rcp_f32_e32 v222, v222
	v_rcp_f32_e32 v223, v223
	v_rcp_f32_e32 v224, v224
	v_rcp_f32_e32 v225, v225
	v_rcp_f32_e32 v226, v226
	v_rcp_f32_e32 v227, v227
	v_rcp_f32_e32 v228, v228
	v_rcp_f32_e32 v229, v229
	v_rcp_f32_e32 v230, v230
	v_rcp_f32_e32 v231, v231
	v_rcp_f32_e32 v232, v232
	v_rcp_f32_e32 v233, v233
	v_pk_mul_f32 v[12:13], v[12:13], v[218:219]
	v_pk_mul_f32 v[14:15], v[14:15], v[220:221]
	v_pk_mul_f32 v[8:9], v[8:9], v[222:223]
	v_pk_mul_f32 v[10:11], v[10:11], v[224:225]
	v_pk_mul_f32 v[4:5], v[4:5], v[226:227]
	v_pk_mul_f32 v[6:7], v[6:7], v[228:229]
	v_pk_mul_f32 v[0:1], v[0:1], v[230:231]
	v_pk_mul_f32 v[2:3], v[2:3], v[232:233]
	v_cvt_pk_bf16_f32 v12, v12, v13
	v_cvt_pk_bf16_f32 v13, v14, v15
	v_cvt_pk_bf16_f32 v14, v8, v9
	v_cvt_pk_bf16_f32 v15, v10, v11
	v_cvt_pk_bf16_f32 v4, v4, v5
	v_cvt_pk_bf16_f32 v5, v6, v7
	v_cvt_pk_bf16_f32 v6, v0, v1
	v_cvt_pk_bf16_f32 v7, v2, v3
	v_add_u32_e32 v140, 0xf2000, v139
	global_store_dwordx4 v140, v[12:15], s[8:9] sc1
	v_add_u32_e32 v141, 0xf2100, v139
	global_store_dwordx4 v141, v[4:7], s[8:9] sc1
	s_branch .LBB0_1021
.Lwin_act_gelu:
	v_pk_mul_f32 v[124:125], v[124:125], v[202:203] op_sel_hi:[1,0]
	v_pk_mul_f32 v[126:127], v[126:127], v[202:203] op_sel_hi:[1,0]
	v_pk_mul_f32 v[120:121], v[120:121], v[202:203] op_sel_hi:[1,0]
	v_pk_mul_f32 v[122:123], v[122:123], v[202:203] op_sel_hi:[1,0]
	v_pk_mul_f32 v[116:117], v[116:117], v[202:203] op_sel_hi:[1,0]
	v_pk_mul_f32 v[118:119], v[118:119], v[202:203] op_sel_hi:[1,0]
	v_pk_mul_f32 v[112:113], v[112:113], v[202:203] op_sel_hi:[1,0]
	v_pk_mul_f32 v[114:115], v[114:115], v[202:203] op_sel_hi:[1,0]
	v_pk_mul_f32 v[218:219], v[124:125], v[134:135] op_sel_hi:[1,0]
	v_pk_mul_f32 v[220:221], v[126:127], v[134:135] op_sel_hi:[1,0]
	v_pk_mul_f32 v[222:223], v[120:121], v[134:135] op_sel_hi:[1,0]
	v_pk_mul_f32 v[224:225], v[122:123], v[134:135] op_sel_hi:[1,0]
	v_pk_mul_f32 v[226:227], v[116:117], v[134:135] op_sel_hi:[1,0]
	v_pk_mul_f32 v[228:229], v[118:119], v[134:135] op_sel_hi:[1,0]
	v_pk_mul_f32 v[230:231], v[112:113], v[134:135] op_sel_hi:[1,0]
	v_pk_mul_f32 v[232:233], v[114:115], v[134:135] op_sel_hi:[1,0]
	v_pk_mul_f32 v[218:219], v[124:125], v[218:219]
	v_pk_mul_f32 v[220:221], v[126:127], v[220:221]
	v_pk_mul_f32 v[222:223], v[120:121], v[222:223]
	v_pk_mul_f32 v[224:225], v[122:123], v[224:225]
	v_pk_mul_f32 v[226:227], v[116:117], v[226:227]
	v_pk_mul_f32 v[228:229], v[118:119], v[228:229]
	v_pk_mul_f32 v[230:231], v[112:113], v[230:231]
	v_pk_mul_f32 v[232:233], v[114:115], v[232:233]
	v_pk_fma_f32 v[218:219], v[124:125], v[218:219], v[124:125]
	v_pk_fma_f32 v[220:221], v[126:127], v[220:221], v[126:127]
	v_pk_fma_f32 v[222:223], v[120:121], v[222:223], v[120:121]
	v_pk_fma_f32 v[224:225], v[122:123], v[224:225], v[122:123]
	v_pk_fma_f32 v[226:227], v[116:117], v[226:227], v[116:117]
	v_pk_fma_f32 v[228:229], v[118:119], v[228:229], v[118:119]
	v_pk_fma_f32 v[230:231], v[112:113], v[230:231], v[112:113]
	v_pk_fma_f32 v[232:233], v[114:115], v[232:233], v[114:115]
	v_pk_mul_f32 v[218:219], v[218:219], v[136:137] op_sel_hi:[1,0]
	v_pk_mul_f32 v[220:221], v[220:221], v[136:137] op_sel_hi:[1,0]
	v_pk_mul_f32 v[222:223], v[222:223], v[136:137] op_sel_hi:[1,0]
	v_pk_mul_f32 v[224:225], v[224:225], v[136:137] op_sel_hi:[1,0]
	v_pk_mul_f32 v[226:227], v[226:227], v[136:137] op_sel_hi:[1,0]
	v_pk_mul_f32 v[228:229], v[228:229], v[136:137] op_sel_hi:[1,0]
	v_pk_mul_f32 v[230:231], v[230:231], v[136:137] op_sel_hi:[1,0]
	v_pk_mul_f32 v[232:233], v[232:233], v[136:137] op_sel_hi:[1,0]
	v_pk_mul_f32 v[218:219], v[218:219], v[132:133] op_sel_hi:[1,0]
	v_pk_mul_f32 v[220:221], v[220:221], v[132:133] op_sel_hi:[1,0]
	v_pk_mul_f32 v[222:223], v[222:223], v[132:133] op_sel_hi:[1,0]
	v_pk_mul_f32 v[224:225], v[224:225], v[132:133] op_sel_hi:[1,0]
	v_pk_mul_f32 v[226:227], v[226:227], v[132:133] op_sel_hi:[1,0]
	v_pk_mul_f32 v[228:229], v[228:229], v[132:133] op_sel_hi:[1,0]
	v_pk_mul_f32 v[230:231], v[230:231], v[132:133] op_sel_hi:[1,0]
	v_pk_mul_f32 v[232:233], v[232:233], v[132:133] op_sel_hi:[1,0]
	v_exp_f32_e32 v218, v218
	v_exp_f32_e32 v219, v219
	v_exp_f32_e32 v220, v220
	v_exp_f32_e32 v221, v221
	v_exp_f32_e32 v222, v222
	v_exp_f32_e32 v223, v223
	v_exp_f32_e32 v224, v224
	v_exp_f32_e32 v225, v225
	v_exp_f32_e32 v226, v226
	v_exp_f32_e32 v227, v227
	v_exp_f32_e32 v228, v228
	v_exp_f32_e32 v229, v229
	v_exp_f32_e32 v230, v230
	v_exp_f32_e32 v231, v231
	v_exp_f32_e32 v232, v232
	v_exp_f32_e32 v233, v233
	v_pk_add_f32 v[218:219], v[218:219], v[128:129]
	v_pk_add_f32 v[220:221], v[220:221], v[128:129]
	v_pk_add_f32 v[222:223], v[222:223], v[128:129]
	v_pk_add_f32 v[224:225], v[224:225], v[128:129]
	v_pk_add_f32 v[226:227], v[226:227], v[128:129]
	v_pk_add_f32 v[228:229], v[228:229], v[128:129]
	v_pk_add_f32 v[230:231], v[230:231], v[128:129]
	v_pk_add_f32 v[232:233], v[232:233], v[128:129]
	v_rcp_f32_e32 v218, v218
	v_rcp_f32_e32 v219, v219
	v_rcp_f32_e32 v220, v220
	v_rcp_f32_e32 v221, v221
	v_rcp_f32_e32 v222, v222
	v_rcp_f32_e32 v223, v223
; __device__ __forceinline__ unsigned pk2(float lo, float hi) { return pg8::cvt_pk_bf16(lo, hi); }
; __device__ __forceinline__ float siluf_(float x) { return x * sigmoidf_(x); }
; __device__ __forceinline__ float geluf_(float x) { const float z = 1.5957691216057308f * (x + 0.044715f * x * x * x); return x * sigmoidf_(z); }
;     __device__ __forceinline__ void operator()(const f32x4 (&acc)[2][2][4][2], const pg8::Unit& u, int wr, int wc, int fr, int fq) const {
;     ...
;             const int act = (pn == 7 || pn == 8) ? 1 : (pn == 10 ? 2 : 0);
; #pragma unroll
;             for (int ai = 0; ai < 2; ++ai)
; #pragma unroll
;                 for (int m = 0; m < 4; ++m) {
;                     const int row = row0 + ai * 128 + m * 16; const float r = rs[ai * 4 + m];
; #pragma unroll
;                     for (int bj = 0; bj < 2; ++bj) {
;                         float v[8];
; #pragma unroll
;                         for (int n = 0; n < 2; ++n)
; #pragma unroll
;                             for (int j = 0; j < 4; ++j) { float t = acc[ai][bj][m][n][j] * r; if (act == 1) t = siluf_(t); else if (act == 2) t = geluf_(t); v[n * 4 + j] = t; }
;                         u32x4 w; w.x = pk2(v[0], v[1]); w.y = pk2(v[2], v[3]); w.z = pk2(v[4], v[5]); w.w = pk2(v[6], v[7]);
;                         *(u32x4*)(Z + (size_t)row * IW + pn * 256 + bj * 128 + wc * 32 + 8 * fq) = w;
;                     }
;                 }
	v_rcp_f32_e32 v224, v224
	v_rcp_f32_e32 v225, v225
	v_rcp_f32_e32 v226, v226
	v_rcp_f32_e32 v227, v227
	v_rcp_f32_e32 v228, v228
	v_rcp_f32_e32 v229, v229
	v_rcp_f32_e32 v230, v230
	v_rcp_f32_e32 v231, v231
	v_rcp_f32_e32 v232, v232
	v_rcp_f32_e32 v233, v233
	v_pk_mul_f32 v[124:125], v[124:125], v[218:219]
	v_pk_mul_f32 v[126:127], v[126:127], v[220:221]
	v_pk_mul_f32 v[120:121], v[120:121], v[222:223]
	v_pk_mul_f32 v[122:123], v[122:123], v[224:225]
	v_pk_mul_f32 v[116:117], v[116:117], v[226:227]
	v_pk_mul_f32 v[118:119], v[118:119], v[228:229]
	v_pk_mul_f32 v[112:113], v[112:113], v[230:231]
	v_pk_mul_f32 v[114:115], v[114:115], v[232:233]
	v_cvt_pk_bf16_f32 v124, v124, v125
	v_cvt_pk_bf16_f32 v125, v126, v127
	v_cvt_pk_bf16_f32 v126, v120, v121
	v_cvt_pk_bf16_f32 v127, v122, v123
	v_cvt_pk_bf16_f32 v116, v116, v117
	v_cvt_pk_bf16_f32 v117, v118, v119
	v_cvt_pk_bf16_f32 v118, v112, v113
	v_cvt_pk_bf16_f32 v119, v114, v115
	v_mov_b32_e32 v140, v139
	global_store_dwordx4 v140, v[124:127], s[8:9] sc1
	v_add_u32_e32 v141, 0x100, v139
	global_store_dwordx4 v141, v[116:119], s[8:9] sc1
	v_pk_mul_f32 v[108:109], v[108:109], v[204:205] op_sel_hi:[1,0]
	v_pk_mul_f32 v[110:111], v[110:111], v[204:205] op_sel_hi:[1,0]
	v_pk_mul_f32 v[104:105], v[104:105], v[204:205] op_sel_hi:[1,0]
	v_pk_mul_f32 v[106:107], v[106:107], v[204:205] op_sel_hi:[1,0]
	v_pk_mul_f32 v[100:101], v[100:101], v[204:205] op_sel_hi:[1,0]
	v_pk_mul_f32 v[102:103], v[102:103], v[204:205] op_sel_hi:[1,0]
	v_pk_mul_f32 v[96:97], v[96:97], v[204:205] op_sel_hi:[1,0]
	v_pk_mul_f32 v[98:99], v[98:99], v[204:205] op_sel_hi:[1,0]
	v_pk_mul_f32 v[218:219], v[108:109], v[134:135] op_sel_hi:[1,0]
	v_pk_mul_f32 v[220:221], v[110:111], v[134:135] op_sel_hi:[1,0]
	v_pk_mul_f32 v[222:223], v[104:105], v[134:135] op_sel_hi:[1,0]
	v_pk_mul_f32 v[224:225], v[106:107], v[134:135] op_sel_hi:[1,0]
	v_pk_mul_f32 v[226:227], v[100:101], v[134:135] op_sel_hi:[1,0]
	v_pk_mul_f32 v[228:229], v[102:103], v[134:135] op_sel_hi:[1,0]
	v_pk_mul_f32 v[230:231], v[96:97], v[134:135] op_sel_hi:[1,0]
	v_pk_mul_f32 v[232:233], v[98:99], v[134:135] op_sel_hi:[1,0]
	v_pk_mul_f32 v[218:219], v[108:109], v[218:219]
	v_pk_mul_f32 v[220:221], v[110:111], v[220:221]
	v_pk_mul_f32 v[222:223], v[104:105], v[222:223]
	v_pk_mul_f32 v[224:225], v[106:107], v[224:225]
	v_pk_mul_f32 v[226:227], v[100:101], v[226:227]
	v_pk_mul_f32 v[228:229], v[102:103], v[228:229]
	v_pk_mul_f32 v[230:231], v[96:97], v[230:231]
	v_pk_mul_f32 v[232:233], v[98:99], v[232:233]
	v_pk_fma_f32 v[218:219], v[108:109], v[218:219], v[108:109]
	v_pk_fma_f32 v[220:221], v[110:111], v[220:221], v[110:111]
	v_pk_fma_f32 v[222:223], v[104:105], v[222:223], v[104:105]
	v_pk_fma_f32 v[224:225], v[106:107], v[224:225], v[106:107]
	v_pk_fma_f32 v[226:227], v[100:101], v[226:227], v[100:101]
	v_pk_fma_f32 v[228:229], v[102:103], v[228:229], v[102:103]
	v_pk_fma_f32 v[230:231], v[96:97], v[230:231], v[96:97]
	v_pk_fma_f32 v[232:233], v[98:99], v[232:233], v[98:99]
	v_pk_mul_f32 v[218:219], v[218:219], v[136:137] op_sel_hi:[1,0]
	v_pk_mul_f32 v[220:221], v[220:221], v[136:137] op_sel_hi:[1,0]
	v_pk_mul_f32 v[222:223], v[222:223], v[136:137] op_sel_hi:[1,0]
	v_pk_mul_f32 v[224:225], v[224:225], v[136:137] op_sel_hi:[1,0]
	v_pk_mul_f32 v[226:227], v[226:227], v[136:137] op_sel_hi:[1,0]
	v_pk_mul_f32 v[228:229], v[228:229], v[136:137] op_sel_hi:[1,0]
	v_pk_mul_f32 v[230:231], v[230:231], v[136:137] op_sel_hi:[1,0]
	v_pk_mul_f32 v[232:233], v[232:233], v[136:137] op_sel_hi:[1,0]
	v_pk_mul_f32 v[218:219], v[218:219], v[132:133] op_sel_hi:[1,0]
	v_pk_mul_f32 v[220:221], v[220:221], v[132:133] op_sel_hi:[1,0]
	v_pk_mul_f32 v[222:223], v[222:223], v[132:133] op_sel_hi:[1,0]
	v_pk_mul_f32 v[224:225], v[224:225], v[132:133] op_sel_hi:[1,0]
	v_pk_mul_f32 v[226:227], v[226:227], v[132:133] op_sel_hi:[1,0]
	v_pk_mul_f32 v[228:229], v[228:229], v[132:133] op_sel_hi:[1,0]
	v_pk_mul_f32 v[230:231], v[230:231], v[132:133] op_sel_hi:[1,0]
	v_pk_mul_f32 v[232:233], v[232:233], v[132:133] op_sel_hi:[1,0]
	v_exp_f32_e32 v218, v218
	v_exp_f32_e32 v219, v219
	v_exp_f32_e32 v220, v220
	v_exp_f32_e32 v221, v221
	v_exp_f32_e32 v222, v222
	v_exp_f32_e32 v223, v223
	v_exp_f32_e32 v224, v224
	v_exp_f32_e32 v225, v225
	v_exp_f32_e32 v226, v226
	v_exp_f32_e32 v227, v227
	v_exp_f32_e32 v228, v228
	v_exp_f32_e32 v229, v229
	v_exp_f32_e32 v230, v230
	v_exp_f32_e32 v231, v231
	v_exp_f32_e32 v232, v232
	v_exp_f32_e32 v233, v233
	v_pk_add_f32 v[218:219], v[218:219], v[128:129]
	v_pk_add_f32 v[220:221], v[220:221], v[128:129]
	v_pk_add_f32 v[222:223], v[222:223], v[128:129]
	v_pk_add_f32 v[224:225], v[224:225], v[128:129]
	v_pk_add_f32 v[226:227], v[226:227], v[128:129]
	v_pk_add_f32 v[228:229], v[228:229], v[128:129]
	v_pk_add_f32 v[230:231], v[230:231], v[128:129]
	v_pk_add_f32 v[232:233], v[232:233], v[128:129]
	v_rcp_f32_e32 v218, v218
	v_rcp_f32_e32 v219, v219
	v_rcp_f32_e32 v220, v220
	v_rcp_f32_e32 v221, v221
	v_rcp_f32_e32 v222, v222
	v_rcp_f32_e32 v223, v223
	v_rcp_f32_e32 v224, v224
	v_rcp_f32_e32 v225, v225
	v_rcp_f32_e32 v226, v226
	v_rcp_f32_e32 v227, v227
	v_rcp_f32_e32 v228, v228
	v_rcp_f32_e32 v229, v229
	v_rcp_f32_e32 v230, v230
	v_rcp_f32_e32 v231, v231
	v_rcp_f32_e32 v232, v232
	v_rcp_f32_e32 v233, v233
	v_pk_mul_f32 v[108:109], v[108:109], v[218:219]
	v_pk_mul_f32 v[110:111], v[110:111], v[220:221]
	v_pk_mul_f32 v[104:105], v[104:105], v[222:223]
	v_pk_mul_f32 v[106:107], v[106:107], v[224:225]
	v_pk_mul_f32 v[100:101], v[100:101], v[226:227]
	v_pk_mul_f32 v[102:103], v[102:103], v[228:229]
	v_pk_mul_f32 v[96:97], v[96:97], v[230:231]
	v_pk_mul_f32 v[98:99], v[98:99], v[232:233]
; __device__ __forceinline__ unsigned pk2(float lo, float hi) { return pg8::cvt_pk_bf16(lo, hi); }
; __device__ __forceinline__ float siluf_(float x) { return x * sigmoidf_(x); }
; __device__ __forceinline__ float geluf_(float x) { const float z = 1.5957691216057308f * (x + 0.044715f * x * x * x); return x * sigmoidf_(z); }
;     __device__ __forceinline__ void operator()(const f32x4 (&acc)[2][2][4][2], const pg8::Unit& u, int wr, int wc, int fr, int fq) const {
;     ...
;             const int act = (pn == 7 || pn == 8) ? 1 : (pn == 10 ? 2 : 0);
; #pragma unroll
;             for (int ai = 0; ai < 2; ++ai)
; #pragma unroll
;                 for (int m = 0; m < 4; ++m) {
;                     const int row = row0 + ai * 128 + m * 16; const float r = rs[ai * 4 + m];
; #pragma unroll
;                     for (int bj = 0; bj < 2; ++bj) {
;                         float v[8];
; #pragma unroll
;                         for (int n = 0; n < 2; ++n)
; #pragma unroll
;                             for (int j = 0; j < 4; ++j) { float t = acc[ai][bj][m][n][j] * r; if (act == 1) t = siluf_(t); else if (act == 2) t = geluf_(t); v[n * 4 + j] = t; }
;                         u32x4 w; w.x = pk2(v[0], v[1]); w.y = pk2(v[2], v[3]); w.z = pk2(v[4], v[5]); w.w = pk2(v[6], v[7]);
;                         *(u32x4*)(Z + (size_t)row * IW + pn * 256 + bj * 128 + wc * 32 + 8 * fq) = w;
;                     }
;                 }
	v_cvt_pk_bf16_f32 v108, v108, v109
	v_cvt_pk_bf16_f32 v109, v110, v111
	v_cvt_pk_bf16_f32 v110, v104, v105
	v_cvt_pk_bf16_f32 v111, v106, v107
	v_cvt_pk_bf16_f32 v100, v100, v101
	v_cvt_pk_bf16_f32 v101, v102, v103
	v_cvt_pk_bf16_f32 v102, v96, v97
	v_cvt_pk_bf16_f32 v103, v98, v99
	v_add_u32_e32 v140, 0x16000, v139
	global_store_dwordx4 v140, v[108:111], s[8:9] sc1
	v_add_u32_e32 v141, 0x16100, v139
	global_store_dwordx4 v141, v[100:103], s[8:9] sc1
	v_pk_mul_f32 v[92:93], v[92:93], v[206:207] op_sel_hi:[1,0]
	v_pk_mul_f32 v[94:95], v[94:95], v[206:207] op_sel_hi:[1,0]
	v_pk_mul_f32 v[88:89], v[88:89], v[206:207] op_sel_hi:[1,0]
	v_pk_mul_f32 v[90:91], v[90:91], v[206:207] op_sel_hi:[1,0]
	v_pk_mul_f32 v[84:85], v[84:85], v[206:207] op_sel_hi:[1,0]
	v_pk_mul_f32 v[86:87], v[86:87], v[206:207] op_sel_hi:[1,0]
	v_pk_mul_f32 v[80:81], v[80:81], v[206:207] op_sel_hi:[1,0]
	v_pk_mul_f32 v[82:83], v[82:83], v[206:207] op_sel_hi:[1,0]
	v_pk_mul_f32 v[218:219], v[92:93], v[134:135] op_sel_hi:[1,0]
	v_pk_mul_f32 v[220:221], v[94:95], v[134:135] op_sel_hi:[1,0]
	v_pk_mul_f32 v[222:223], v[88:89], v[134:135] op_sel_hi:[1,0]
	v_pk_mul_f32 v[224:225], v[90:91], v[134:135] op_sel_hi:[1,0]
	v_pk_mul_f32 v[226:227], v[84:85], v[134:135] op_sel_hi:[1,0]
	v_pk_mul_f32 v[228:229], v[86:87], v[134:135] op_sel_hi:[1,0]
	v_pk_mul_f32 v[230:231], v[80:81], v[134:135] op_sel_hi:[1,0]
	v_pk_mul_f32 v[232:233], v[82:83], v[134:135] op_sel_hi:[1,0]
	v_pk_mul_f32 v[218:219], v[92:93], v[218:219]
	v_pk_mul_f32 v[220:221], v[94:95], v[220:221]
	v_pk_mul_f32 v[222:223], v[88:89], v[222:223]
	v_pk_mul_f32 v[224:225], v[90:91], v[224:225]
	v_pk_mul_f32 v[226:227], v[84:85], v[226:227]
	v_pk_mul_f32 v[228:229], v[86:87], v[228:229]
	v_pk_mul_f32 v[230:231], v[80:81], v[230:231]
	v_pk_mul_f32 v[232:233], v[82:83], v[232:233]
	v_pk_fma_f32 v[218:219], v[92:93], v[218:219], v[92:93]
	v_pk_fma_f32 v[220:221], v[94:95], v[220:221], v[94:95]
	v_pk_fma_f32 v[222:223], v[88:89], v[222:223], v[88:89]
	v_pk_fma_f32 v[224:225], v[90:91], v[224:225], v[90:91]
	v_pk_fma_f32 v[226:227], v[84:85], v[226:227], v[84:85]
	v_pk_fma_f32 v[228:229], v[86:87], v[228:229], v[86:87]
	v_pk_fma_f32 v[230:231], v[80:81], v[230:231], v[80:81]
	v_pk_fma_f32 v[232:233], v[82:83], v[232:233], v[82:83]
	v_pk_mul_f32 v[218:219], v[218:219], v[136:137] op_sel_hi:[1,0]
	v_pk_mul_f32 v[220:221], v[220:221], v[136:137] op_sel_hi:[1,0]
	v_pk_mul_f32 v[222:223], v[222:223], v[136:137] op_sel_hi:[1,0]
	v_pk_mul_f32 v[224:225], v[224:225], v[136:137] op_sel_hi:[1,0]
	v_pk_mul_f32 v[226:227], v[226:227], v[136:137] op_sel_hi:[1,0]
	v_pk_mul_f32 v[228:229], v[228:229], v[136:137] op_sel_hi:[1,0]
	v_pk_mul_f32 v[230:231], v[230:231], v[136:137] op_sel_hi:[1,0]
	v_pk_mul_f32 v[232:233], v[232:233], v[136:137] op_sel_hi:[1,0]
	v_pk_mul_f32 v[218:219], v[218:219], v[132:133] op_sel_hi:[1,0]
	v_pk_mul_f32 v[220:221], v[220:221], v[132:133] op_sel_hi:[1,0]
	v_pk_mul_f32 v[222:223], v[222:223], v[132:133] op_sel_hi:[1,0]
	v_pk_mul_f32 v[224:225], v[224:225], v[132:133] op_sel_hi:[1,0]
	v_pk_mul_f32 v[226:227], v[226:227], v[132:133] op_sel_hi:[1,0]
	v_pk_mul_f32 v[228:229], v[228:229], v[132:133] op_sel_hi:[1,0]
	v_pk_mul_f32 v[230:231], v[230:231], v[132:133] op_sel_hi:[1,0]
	v_pk_mul_f32 v[232:233], v[232:233], v[132:133] op_sel_hi:[1,0]
	v_exp_f32_e32 v218, v218
	v_exp_f32_e32 v219, v219
	v_exp_f32_e32 v220, v220
	v_exp_f32_e32 v221, v221
	v_exp_f32_e32 v222, v222
	v_exp_f32_e32 v223, v223
	v_exp_f32_e32 v224, v224
	v_exp_f32_e32 v225, v225
	v_exp_f32_e32 v226, v226
	v_exp_f32_e32 v227, v227
	v_exp_f32_e32 v228, v228
	v_exp_f32_e32 v229, v229
	v_exp_f32_e32 v230, v230
	v_exp_f32_e32 v231, v231
	v_exp_f32_e32 v232, v232
	v_exp_f32_e32 v233, v233
	v_pk_add_f32 v[218:219], v[218:219], v[128:129]
	v_pk_add_f32 v[220:221], v[220:221], v[128:129]
	v_pk_add_f32 v[222:223], v[222:223], v[128:129]
	v_pk_add_f32 v[224:225], v[224:225], v[128:129]
	v_pk_add_f32 v[226:227], v[226:227], v[128:129]
	v_pk_add_f32 v[228:229], v[228:229], v[128:129]
	v_pk_add_f32 v[230:231], v[230:231], v[128:129]
	v_pk_add_f32 v[232:233], v[232:233], v[128:129]
	v_rcp_f32_e32 v218, v218
	v_rcp_f32_e32 v219, v219
	v_rcp_f32_e32 v220, v220
	v_rcp_f32_e32 v221, v221
	v_rcp_f32_e32 v222, v222
	v_rcp_f32_e32 v223, v223
	v_rcp_f32_e32 v224, v224
	v_rcp_f32_e32 v225, v225
	v_rcp_f32_e32 v226, v226
	v_rcp_f32_e32 v227, v227
	v_rcp_f32_e32 v228, v228
	v_rcp_f32_e32 v229, v229
	v_rcp_f32_e32 v230, v230
	v_rcp_f32_e32 v231, v231
	v_rcp_f32_e32 v232, v232
	v_rcp_f32_e32 v233, v233
	v_pk_mul_f32 v[92:93], v[92:93], v[218:219]
	v_pk_mul_f32 v[94:95], v[94:95], v[220:221]
	v_pk_mul_f32 v[88:89], v[88:89], v[222:223]
	v_pk_mul_f32 v[90:91], v[90:91], v[224:225]
	v_pk_mul_f32 v[84:85], v[84:85], v[226:227]
	v_pk_mul_f32 v[86:87], v[86:87], v[228:229]
	v_pk_mul_f32 v[80:81], v[80:81], v[230:231]
	v_pk_mul_f32 v[82:83], v[82:83], v[232:233]
	v_cvt_pk_bf16_f32 v92, v92, v93
	v_cvt_pk_bf16_f32 v93, v94, v95
	v_cvt_pk_bf16_f32 v94, v88, v89
	v_cvt_pk_bf16_f32 v95, v90, v91
	v_cvt_pk_bf16_f32 v84, v84, v85
	v_cvt_pk_bf16_f32 v85, v86, v87
	v_cvt_pk_bf16_f32 v86, v80, v81
	v_cvt_pk_bf16_f32 v87, v82, v83
	v_add_u32_e32 v140, 0x2c000, v139
	global_store_dwordx4 v140, v[92:95], s[8:9] sc1
	v_add_u32_e32 v141, 0x2c100, v139
	global_store_dwordx4 v141, v[84:87], s[8:9] sc1
	v_pk_mul_f32 v[76:77], v[76:77], v[208:209] op_sel_hi:[1,0]
	v_pk_mul_f32 v[78:79], v[78:79], v[208:209] op_sel_hi:[1,0]
	v_pk_mul_f32 v[72:73], v[72:73], v[208:209] op_sel_hi:[1,0]
	v_pk_mul_f32 v[74:75], v[74:75], v[208:209] op_sel_hi:[1,0]
	v_pk_mul_f32 v[68:69], v[68:69], v[208:209] op_sel_hi:[1,0]
; __device__ __forceinline__ unsigned pk2(float lo, float hi) { return pg8::cvt_pk_bf16(lo, hi); }
; __device__ __forceinline__ float siluf_(float x) { return x * sigmoidf_(x); }
; __device__ __forceinline__ float geluf_(float x) { const float z = 1.5957691216057308f * (x + 0.044715f * x * x * x); return x * sigmoidf_(z); }
;     __device__ __forceinline__ void operator()(const f32x4 (&acc)[2][2][4][2], const pg8::Unit& u, int wr, int wc, int fr, int fq) const {
;     ...
;             const int act = (pn == 7 || pn == 8) ? 1 : (pn == 10 ? 2 : 0);
; #pragma unroll
;             for (int ai = 0; ai < 2; ++ai)
; #pragma unroll
;                 for (int m = 0; m < 4; ++m) {
;                     const int row = row0 + ai * 128 + m * 16; const float r = rs[ai * 4 + m];
; #pragma unroll
;                     for (int bj = 0; bj < 2; ++bj) {
;                         float v[8];
; #pragma unroll
;                         for (int n = 0; n < 2; ++n)
; #pragma unroll
;                             for (int j = 0; j < 4; ++j) { float t = acc[ai][bj][m][n][j] * r; if (act == 1) t = siluf_(t); else if (act == 2) t = geluf_(t); v[n * 4 + j] = t; }
;                         u32x4 w; w.x = pk2(v[0], v[1]); w.y = pk2(v[2], v[3]); w.z = pk2(v[4], v[5]); w.w = pk2(v[6], v[7]);
;                         *(u32x4*)(Z + (size_t)row * IW + pn * 256 + bj * 128 + wc * 32 + 8 * fq) = w;
;                     }
;                 }
	v_pk_mul_f32 v[70:71], v[70:71], v[208:209] op_sel_hi:[1,0]
	v_pk_mul_f32 v[64:65], v[64:65], v[208:209] op_sel_hi:[1,0]
	v_pk_mul_f32 v[66:67], v[66:67], v[208:209] op_sel_hi:[1,0]
	v_pk_mul_f32 v[218:219], v[76:77], v[134:135] op_sel_hi:[1,0]
	v_pk_mul_f32 v[220:221], v[78:79], v[134:135] op_sel_hi:[1,0]
	v_pk_mul_f32 v[222:223], v[72:73], v[134:135] op_sel_hi:[1,0]
	v_pk_mul_f32 v[224:225], v[74:75], v[134:135] op_sel_hi:[1,0]
	v_pk_mul_f32 v[226:227], v[68:69], v[134:135] op_sel_hi:[1,0]
	v_pk_mul_f32 v[228:229], v[70:71], v[134:135] op_sel_hi:[1,0]
	v_pk_mul_f32 v[230:231], v[64:65], v[134:135] op_sel_hi:[1,0]
	v_pk_mul_f32 v[232:233], v[66:67], v[134:135] op_sel_hi:[1,0]
	v_pk_mul_f32 v[218:219], v[76:77], v[218:219]
	v_pk_mul_f32 v[220:221], v[78:79], v[220:221]
	v_pk_mul_f32 v[222:223], v[72:73], v[222:223]
	v_pk_mul_f32 v[224:225], v[74:75], v[224:225]
	v_pk_mul_f32 v[226:227], v[68:69], v[226:227]
	v_pk_mul_f32 v[228:229], v[70:71], v[228:229]
	v_pk_mul_f32 v[230:231], v[64:65], v[230:231]
	v_pk_mul_f32 v[232:233], v[66:67], v[232:233]
	v_pk_fma_f32 v[218:219], v[76:77], v[218:219], v[76:77]
	v_pk_fma_f32 v[220:221], v[78:79], v[220:221], v[78:79]
	v_pk_fma_f32 v[222:223], v[72:73], v[222:223], v[72:73]
	v_pk_fma_f32 v[224:225], v[74:75], v[224:225], v[74:75]
	v_pk_fma_f32 v[226:227], v[68:69], v[226:227], v[68:69]
	v_pk_fma_f32 v[228:229], v[70:71], v[228:229], v[70:71]
	v_pk_fma_f32 v[230:231], v[64:65], v[230:231], v[64:65]
	v_pk_fma_f32 v[232:233], v[66:67], v[232:233], v[66:67]
	v_pk_mul_f32 v[218:219], v[218:219], v[136:137] op_sel_hi:[1,0]
	v_pk_mul_f32 v[220:221], v[220:221], v[136:137] op_sel_hi:[1,0]
	v_pk_mul_f32 v[222:223], v[222:223], v[136:137] op_sel_hi:[1,0]
	v_pk_mul_f32 v[224:225], v[224:225], v[136:137] op_sel_hi:[1,0]
	v_pk_mul_f32 v[226:227], v[226:227], v[136:137] op_sel_hi:[1,0]
	v_pk_mul_f32 v[228:229], v[228:229], v[136:137] op_sel_hi:[1,0]
	v_pk_mul_f32 v[230:231], v[230:231], v[136:137] op_sel_hi:[1,0]
	v_pk_mul_f32 v[232:233], v[232:233], v[136:137] op_sel_hi:[1,0]
	v_pk_mul_f32 v[218:219], v[218:219], v[132:133] op_sel_hi:[1,0]
	v_pk_mul_f32 v[220:221], v[220:221], v[132:133] op_sel_hi:[1,0]
	v_pk_mul_f32 v[222:223], v[222:223], v[132:133] op_sel_hi:[1,0]
	v_pk_mul_f32 v[224:225], v[224:225], v[132:133] op_sel_hi:[1,0]
	v_pk_mul_f32 v[226:227], v[226:227], v[132:133] op_sel_hi:[1,0]
	v_pk_mul_f32 v[228:229], v[228:229], v[132:133] op_sel_hi:[1,0]
	v_pk_mul_f32 v[230:231], v[230:231], v[132:133] op_sel_hi:[1,0]
	v_pk_mul_f32 v[232:233], v[232:233], v[132:133] op_sel_hi:[1,0]
	v_exp_f32_e32 v218, v218
	v_exp_f32_e32 v219, v219
	v_exp_f32_e32 v220, v220
	v_exp_f32_e32 v221, v221
	v_exp_f32_e32 v222, v222
	v_exp_f32_e32 v223, v223
	v_exp_f32_e32 v224, v224
	v_exp_f32_e32 v225, v225
	v_exp_f32_e32 v226, v226
	v_exp_f32_e32 v227, v227
	v_exp_f32_e32 v228, v228
	v_exp_f32_e32 v229, v229
	v_exp_f32_e32 v230, v230
	v_exp_f32_e32 v231, v231
	v_exp_f32_e32 v232, v232
	v_exp_f32_e32 v233, v233
	v_pk_add_f32 v[218:219], v[218:219], v[128:129]
	v_pk_add_f32 v[220:221], v[220:221], v[128:129]
	v_pk_add_f32 v[222:223], v[222:223], v[128:129]
	v_pk_add_f32 v[224:225], v[224:225], v[128:129]
	v_pk_add_f32 v[226:227], v[226:227], v[128:129]
	v_pk_add_f32 v[228:229], v[228:229], v[128:129]
	v_pk_add_f32 v[230:231], v[230:231], v[128:129]
	v_pk_add_f32 v[232:233], v[232:233], v[128:129]
	v_rcp_f32_e32 v218, v218
	v_rcp_f32_e32 v219, v219
	v_rcp_f32_e32 v220, v220
	v_rcp_f32_e32 v221, v221
	v_rcp_f32_e32 v222, v222
	v_rcp_f32_e32 v223, v223
	v_rcp_f32_e32 v224, v224
	v_rcp_f32_e32 v225, v225
	v_rcp_f32_e32 v226, v226
	v_rcp_f32_e32 v227, v227
	v_rcp_f32_e32 v228, v228
	v_rcp_f32_e32 v229, v229
	v_rcp_f32_e32 v230, v230
	v_rcp_f32_e32 v231, v231
	v_rcp_f32_e32 v232, v232
	v_rcp_f32_e32 v233, v233
	v_pk_mul_f32 v[76:77], v[76:77], v[218:219]
	v_pk_mul_f32 v[78:79], v[78:79], v[220:221]
	v_pk_mul_f32 v[72:73], v[72:73], v[222:223]
	v_pk_mul_f32 v[74:75], v[74:75], v[224:225]
	v_pk_mul_f32 v[68:69], v[68:69], v[226:227]
	v_pk_mul_f32 v[70:71], v[70:71], v[228:229]
	v_pk_mul_f32 v[64:65], v[64:65], v[230:231]
	v_pk_mul_f32 v[66:67], v[66:67], v[232:233]
	v_cvt_pk_bf16_f32 v76, v76, v77
	v_cvt_pk_bf16_f32 v77, v78, v79
	v_cvt_pk_bf16_f32 v78, v72, v73
	v_cvt_pk_bf16_f32 v79, v74, v75
	v_cvt_pk_bf16_f32 v68, v68, v69
	v_cvt_pk_bf16_f32 v69, v70, v71
	v_cvt_pk_bf16_f32 v70, v64, v65
	v_cvt_pk_bf16_f32 v71, v66, v67
	v_add_u32_e32 v140, 0x42000, v139
	global_store_dwordx4 v140, v[76:79], s[8:9] sc1
	v_add_u32_e32 v141, 0x42100, v139
	global_store_dwordx4 v141, v[68:71], s[8:9] sc1
	v_pk_mul_f32 v[60:61], v[60:61], v[210:211] op_sel_hi:[1,0]
	v_pk_mul_f32 v[62:63], v[62:63], v[210:211] op_sel_hi:[1,0]
	v_pk_mul_f32 v[56:57], v[56:57], v[210:211] op_sel_hi:[1,0]
	v_pk_mul_f32 v[58:59], v[58:59], v[210:211] op_sel_hi:[1,0]
	v_pk_mul_f32 v[52:53], v[52:53], v[210:211] op_sel_hi:[1,0]
	v_pk_mul_f32 v[54:55], v[54:55], v[210:211] op_sel_hi:[1,0]
	v_pk_mul_f32 v[48:49], v[48:49], v[210:211] op_sel_hi:[1,0]
	v_pk_mul_f32 v[50:51], v[50:51], v[210:211] op_sel_hi:[1,0]
	v_pk_mul_f32 v[218:219], v[60:61], v[134:135] op_sel_hi:[1,0]
	v_pk_mul_f32 v[220:221], v[62:63], v[134:135] op_sel_hi:[1,0]
	v_pk_mul_f32 v[222:223], v[56:57], v[134:135] op_sel_hi:[1,0]
	v_pk_mul_f32 v[224:225], v[58:59], v[134:135] op_sel_hi:[1,0]
	v_pk_mul_f32 v[226:227], v[52:53], v[134:135] op_sel_hi:[1,0]
	v_pk_mul_f32 v[228:229], v[54:55], v[134:135] op_sel_hi:[1,0]
	v_pk_mul_f32 v[230:231], v[48:49], v[134:135] op_sel_hi:[1,0]
	v_pk_mul_f32 v[232:233], v[50:51], v[134:135] op_sel_hi:[1,0]
	v_pk_mul_f32 v[218:219], v[60:61], v[218:219]
	v_pk_mul_f32 v[220:221], v[62:63], v[220:221]
; __device__ __forceinline__ unsigned pk2(float lo, float hi) { return pg8::cvt_pk_bf16(lo, hi); }
; __device__ __forceinline__ float siluf_(float x) { return x * sigmoidf_(x); }
; __device__ __forceinline__ float geluf_(float x) { const float z = 1.5957691216057308f * (x + 0.044715f * x * x * x); return x * sigmoidf_(z); }
;     __device__ __forceinline__ void operator()(const f32x4 (&acc)[2][2][4][2], const pg8::Unit& u, int wr, int wc, int fr, int fq) const {
;     ...
;             const int act = (pn == 7 || pn == 8) ? 1 : (pn == 10 ? 2 : 0);
; #pragma unroll
;             for (int ai = 0; ai < 2; ++ai)
; #pragma unroll
;                 for (int m = 0; m < 4; ++m) {
;                     const int row = row0 + ai * 128 + m * 16; const float r = rs[ai * 4 + m];
; #pragma unroll
;                     for (int bj = 0; bj < 2; ++bj) {
;                         float v[8];
; #pragma unroll
;                         for (int n = 0; n < 2; ++n)
; #pragma unroll
;                             for (int j = 0; j < 4; ++j) { float t = acc[ai][bj][m][n][j] * r; if (act == 1) t = siluf_(t); else if (act == 2) t = geluf_(t); v[n * 4 + j] = t; }
;                         u32x4 w; w.x = pk2(v[0], v[1]); w.y = pk2(v[2], v[3]); w.z = pk2(v[4], v[5]); w.w = pk2(v[6], v[7]);
;                         *(u32x4*)(Z + (size_t)row * IW + pn * 256 + bj * 128 + wc * 32 + 8 * fq) = w;
;                     }
;                 }
	v_pk_mul_f32 v[222:223], v[56:57], v[222:223]
	v_pk_mul_f32 v[224:225], v[58:59], v[224:225]
	v_pk_mul_f32 v[226:227], v[52:53], v[226:227]
	v_pk_mul_f32 v[228:229], v[54:55], v[228:229]
	v_pk_mul_f32 v[230:231], v[48:49], v[230:231]
	v_pk_mul_f32 v[232:233], v[50:51], v[232:233]
	v_pk_fma_f32 v[218:219], v[60:61], v[218:219], v[60:61]
	v_pk_fma_f32 v[220:221], v[62:63], v[220:221], v[62:63]
	v_pk_fma_f32 v[222:223], v[56:57], v[222:223], v[56:57]
	v_pk_fma_f32 v[224:225], v[58:59], v[224:225], v[58:59]
	v_pk_fma_f32 v[226:227], v[52:53], v[226:227], v[52:53]
	v_pk_fma_f32 v[228:229], v[54:55], v[228:229], v[54:55]
	v_pk_fma_f32 v[230:231], v[48:49], v[230:231], v[48:49]
	v_pk_fma_f32 v[232:233], v[50:51], v[232:233], v[50:51]
	v_pk_mul_f32 v[218:219], v[218:219], v[136:137] op_sel_hi:[1,0]
	v_pk_mul_f32 v[220:221], v[220:221], v[136:137] op_sel_hi:[1,0]
	v_pk_mul_f32 v[222:223], v[222:223], v[136:137] op_sel_hi:[1,0]
	v_pk_mul_f32 v[224:225], v[224:225], v[136:137] op_sel_hi:[1,0]
	v_pk_mul_f32 v[226:227], v[226:227], v[136:137] op_sel_hi:[1,0]
	v_pk_mul_f32 v[228:229], v[228:229], v[136:137] op_sel_hi:[1,0]
	v_pk_mul_f32 v[230:231], v[230:231], v[136:137] op_sel_hi:[1,0]
	v_pk_mul_f32 v[232:233], v[232:233], v[136:137] op_sel_hi:[1,0]
	v_pk_mul_f32 v[218:219], v[218:219], v[132:133] op_sel_hi:[1,0]
	v_pk_mul_f32 v[220:221], v[220:221], v[132:133] op_sel_hi:[1,0]
	v_pk_mul_f32 v[222:223], v[222:223], v[132:133] op_sel_hi:[1,0]
	v_pk_mul_f32 v[224:225], v[224:225], v[132:133] op_sel_hi:[1,0]
	v_pk_mul_f32 v[226:227], v[226:227], v[132:133] op_sel_hi:[1,0]
	v_pk_mul_f32 v[228:229], v[228:229], v[132:133] op_sel_hi:[1,0]
	v_pk_mul_f32 v[230:231], v[230:231], v[132:133] op_sel_hi:[1,0]
	v_pk_mul_f32 v[232:233], v[232:233], v[132:133] op_sel_hi:[1,0]
	v_exp_f32_e32 v218, v218
	v_exp_f32_e32 v219, v219
	v_exp_f32_e32 v220, v220
	v_exp_f32_e32 v221, v221
	v_exp_f32_e32 v222, v222
	v_exp_f32_e32 v223, v223
	v_exp_f32_e32 v224, v224
	v_exp_f32_e32 v225, v225
	v_exp_f32_e32 v226, v226
	v_exp_f32_e32 v227, v227
	v_exp_f32_e32 v228, v228
	v_exp_f32_e32 v229, v229
	v_exp_f32_e32 v230, v230
	v_exp_f32_e32 v231, v231
	v_exp_f32_e32 v232, v232
	v_exp_f32_e32 v233, v233
	v_pk_add_f32 v[218:219], v[218:219], v[128:129]
	v_pk_add_f32 v[220:221], v[220:221], v[128:129]
	v_pk_add_f32 v[222:223], v[222:223], v[128:129]
	v_pk_add_f32 v[224:225], v[224:225], v[128:129]
	v_pk_add_f32 v[226:227], v[226:227], v[128:129]
	v_pk_add_f32 v[228:229], v[228:229], v[128:129]
	v_pk_add_f32 v[230:231], v[230:231], v[128:129]
	v_pk_add_f32 v[232:233], v[232:233], v[128:129]
	v_rcp_f32_e32 v218, v218
	v_rcp_f32_e32 v219, v219
	v_rcp_f32_e32 v220, v220
	v_rcp_f32_e32 v221, v221
	v_rcp_f32_e32 v222, v222
	v_rcp_f32_e32 v223, v223
	v_rcp_f32_e32 v224, v224
	v_rcp_f32_e32 v225, v225
	v_rcp_f32_e32 v226, v226
	v_rcp_f32_e32 v227, v227
	v_rcp_f32_e32 v228, v228
	v_rcp_f32_e32 v229, v229
	v_rcp_f32_e32 v230, v230
	v_rcp_f32_e32 v231, v231
	v_rcp_f32_e32 v232, v232
	v_rcp_f32_e32 v233, v233
	v_pk_mul_f32 v[60:61], v[60:61], v[218:219]
	v_pk_mul_f32 v[62:63], v[62:63], v[220:221]
	v_pk_mul_f32 v[56:57], v[56:57], v[222:223]
	v_pk_mul_f32 v[58:59], v[58:59], v[224:225]
	v_pk_mul_f32 v[52:53], v[52:53], v[226:227]
	v_pk_mul_f32 v[54:55], v[54:55], v[228:229]
	v_pk_mul_f32 v[48:49], v[48:49], v[230:231]
	v_pk_mul_f32 v[50:51], v[50:51], v[232:233]
	v_cvt_pk_bf16_f32 v60, v60, v61
	v_cvt_pk_bf16_f32 v61, v62, v63
	v_cvt_pk_bf16_f32 v62, v56, v57
	v_cvt_pk_bf16_f32 v63, v58, v59
	v_cvt_pk_bf16_f32 v52, v52, v53
	v_cvt_pk_bf16_f32 v53, v54, v55
	v_cvt_pk_bf16_f32 v54, v48, v49
	v_cvt_pk_bf16_f32 v55, v50, v51
	v_add_u32_e32 v140, 0xb0000, v139
	global_store_dwordx4 v140, v[60:63], s[8:9] sc1
	v_add_u32_e32 v141, 0xb0100, v139
	global_store_dwordx4 v141, v[52:55], s[8:9] sc1
	v_pk_mul_f32 v[44:45], v[44:45], v[212:213] op_sel_hi:[1,0]
	v_pk_mul_f32 v[46:47], v[46:47], v[212:213] op_sel_hi:[1,0]
	v_pk_mul_f32 v[40:41], v[40:41], v[212:213] op_sel_hi:[1,0]
	v_pk_mul_f32 v[42:43], v[42:43], v[212:213] op_sel_hi:[1,0]
	v_pk_mul_f32 v[36:37], v[36:37], v[212:213] op_sel_hi:[1,0]
	v_pk_mul_f32 v[38:39], v[38:39], v[212:213] op_sel_hi:[1,0]
	v_pk_mul_f32 v[32:33], v[32:33], v[212:213] op_sel_hi:[1,0]
	v_pk_mul_f32 v[34:35], v[34:35], v[212:213] op_sel_hi:[1,0]
	v_pk_mul_f32 v[218:219], v[44:45], v[134:135] op_sel_hi:[1,0]
	v_pk_mul_f32 v[220:221], v[46:47], v[134:135] op_sel_hi:[1,0]
	v_pk_mul_f32 v[222:223], v[40:41], v[134:135] op_sel_hi:[1,0]
	v_pk_mul_f32 v[224:225], v[42:43], v[134:135] op_sel_hi:[1,0]
	v_pk_mul_f32 v[226:227], v[36:37], v[134:135] op_sel_hi:[1,0]
	v_pk_mul_f32 v[228:229], v[38:39], v[134:135] op_sel_hi:[1,0]
	v_pk_mul_f32 v[230:231], v[32:33], v[134:135] op_sel_hi:[1,0]
	v_pk_mul_f32 v[232:233], v[34:35], v[134:135] op_sel_hi:[1,0]
	v_pk_mul_f32 v[218:219], v[44:45], v[218:219]
	v_pk_mul_f32 v[220:221], v[46:47], v[220:221]
	v_pk_mul_f32 v[222:223], v[40:41], v[222:223]
	v_pk_mul_f32 v[224:225], v[42:43], v[224:225]
	v_pk_mul_f32 v[226:227], v[36:37], v[226:227]
	v_pk_mul_f32 v[228:229], v[38:39], v[228:229]
	v_pk_mul_f32 v[230:231], v[32:33], v[230:231]
	v_pk_mul_f32 v[232:233], v[34:35], v[232:233]
	v_pk_fma_f32 v[218:219], v[44:45], v[218:219], v[44:45]
	v_pk_fma_f32 v[220:221], v[46:47], v[220:221], v[46:47]
	v_pk_fma_f32 v[222:223], v[40:41], v[222:223], v[40:41]
	v_pk_fma_f32 v[224:225], v[42:43], v[224:225], v[42:43]
	v_pk_fma_f32 v[226:227], v[36:37], v[226:227], v[36:37]
	v_pk_fma_f32 v[228:229], v[38:39], v[228:229], v[38:39]
	v_pk_fma_f32 v[230:231], v[32:33], v[230:231], v[32:33]
	v_pk_fma_f32 v[232:233], v[34:35], v[232:233], v[34:35]
; __device__ __forceinline__ unsigned pk2(float lo, float hi) { return pg8::cvt_pk_bf16(lo, hi); }
; __device__ __forceinline__ float siluf_(float x) { return x * sigmoidf_(x); }
; __device__ __forceinline__ float geluf_(float x) { const float z = 1.5957691216057308f * (x + 0.044715f * x * x * x); return x * sigmoidf_(z); }
;     __device__ __forceinline__ void operator()(const f32x4 (&acc)[2][2][4][2], const pg8::Unit& u, int wr, int wc, int fr, int fq) const {
;     ...
;             const int act = (pn == 7 || pn == 8) ? 1 : (pn == 10 ? 2 : 0);
; #pragma unroll
;             for (int ai = 0; ai < 2; ++ai)
; #pragma unroll
;                 for (int m = 0; m < 4; ++m) {
;                     const int row = row0 + ai * 128 + m * 16; const float r = rs[ai * 4 + m];
; #pragma unroll
;                     for (int bj = 0; bj < 2; ++bj) {
;                         float v[8];
; #pragma unroll
;                         for (int n = 0; n < 2; ++n)
; #pragma unroll
;                             for (int j = 0; j < 4; ++j) { float t = acc[ai][bj][m][n][j] * r; if (act == 1) t = siluf_(t); else if (act == 2) t = geluf_(t); v[n * 4 + j] = t; }
;                         u32x4 w; w.x = pk2(v[0], v[1]); w.y = pk2(v[2], v[3]); w.z = pk2(v[4], v[5]); w.w = pk2(v[6], v[7]);
;                         *(u32x4*)(Z + (size_t)row * IW + pn * 256 + bj * 128 + wc * 32 + 8 * fq) = w;
;                     }
;                 }
	v_pk_mul_f32 v[218:219], v[218:219], v[136:137] op_sel_hi:[1,0]
	v_pk_mul_f32 v[220:221], v[220:221], v[136:137] op_sel_hi:[1,0]
	v_pk_mul_f32 v[222:223], v[222:223], v[136:137] op_sel_hi:[1,0]
	v_pk_mul_f32 v[224:225], v[224:225], v[136:137] op_sel_hi:[1,0]
	v_pk_mul_f32 v[226:227], v[226:227], v[136:137] op_sel_hi:[1,0]
	v_pk_mul_f32 v[228:229], v[228:229], v[136:137] op_sel_hi:[1,0]
	v_pk_mul_f32 v[230:231], v[230:231], v[136:137] op_sel_hi:[1,0]
	v_pk_mul_f32 v[232:233], v[232:233], v[136:137] op_sel_hi:[1,0]
	v_pk_mul_f32 v[218:219], v[218:219], v[132:133] op_sel_hi:[1,0]
	v_pk_mul_f32 v[220:221], v[220:221], v[132:133] op_sel_hi:[1,0]
	v_pk_mul_f32 v[222:223], v[222:223], v[132:133] op_sel_hi:[1,0]
	v_pk_mul_f32 v[224:225], v[224:225], v[132:133] op_sel_hi:[1,0]
	v_pk_mul_f32 v[226:227], v[226:227], v[132:133] op_sel_hi:[1,0]
	v_pk_mul_f32 v[228:229], v[228:229], v[132:133] op_sel_hi:[1,0]
	v_pk_mul_f32 v[230:231], v[230:231], v[132:133] op_sel_hi:[1,0]
	v_pk_mul_f32 v[232:233], v[232:233], v[132:133] op_sel_hi:[1,0]
	v_exp_f32_e32 v218, v218
	v_exp_f32_e32 v219, v219
	v_exp_f32_e32 v220, v220
	v_exp_f32_e32 v221, v221
	v_exp_f32_e32 v222, v222
	v_exp_f32_e32 v223, v223
	v_exp_f32_e32 v224, v224
	v_exp_f32_e32 v225, v225
	v_exp_f32_e32 v226, v226
	v_exp_f32_e32 v227, v227
	v_exp_f32_e32 v228, v228
	v_exp_f32_e32 v229, v229
	v_exp_f32_e32 v230, v230
	v_exp_f32_e32 v231, v231
	v_exp_f32_e32 v232, v232
	v_exp_f32_e32 v233, v233
	v_pk_add_f32 v[218:219], v[218:219], v[128:129]
	v_pk_add_f32 v[220:221], v[220:221], v[128:129]
	v_pk_add_f32 v[222:223], v[222:223], v[128:129]
	v_pk_add_f32 v[224:225], v[224:225], v[128:129]
	v_pk_add_f32 v[226:227], v[226:227], v[128:129]
	v_pk_add_f32 v[228:229], v[228:229], v[128:129]
	v_pk_add_f32 v[230:231], v[230:231], v[128:129]
	v_pk_add_f32 v[232:233], v[232:233], v[128:129]
	v_rcp_f32_e32 v218, v218
	v_rcp_f32_e32 v219, v219
	v_rcp_f32_e32 v220, v220
	v_rcp_f32_e32 v221, v221
	v_rcp_f32_e32 v222, v222
	v_rcp_f32_e32 v223, v223
	v_rcp_f32_e32 v224, v224
	v_rcp_f32_e32 v225, v225
	v_rcp_f32_e32 v226, v226
	v_rcp_f32_e32 v227, v227
	v_rcp_f32_e32 v228, v228
	v_rcp_f32_e32 v229, v229
	v_rcp_f32_e32 v230, v230
	v_rcp_f32_e32 v231, v231
	v_rcp_f32_e32 v232, v232
	v_rcp_f32_e32 v233, v233
	v_pk_mul_f32 v[44:45], v[44:45], v[218:219]
	v_pk_mul_f32 v[46:47], v[46:47], v[220:221]
	v_pk_mul_f32 v[40:41], v[40:41], v[222:223]
	v_pk_mul_f32 v[42:43], v[42:43], v[224:225]
	v_pk_mul_f32 v[36:37], v[36:37], v[226:227]
	v_pk_mul_f32 v[38:39], v[38:39], v[228:229]
	v_pk_mul_f32 v[32:33], v[32:33], v[230:231]
	v_pk_mul_f32 v[34:35], v[34:35], v[232:233]
	v_cvt_pk_bf16_f32 v44, v44, v45
	v_cvt_pk_bf16_f32 v45, v46, v47
	v_cvt_pk_bf16_f32 v46, v40, v41
	v_cvt_pk_bf16_f32 v47, v42, v43
	v_cvt_pk_bf16_f32 v36, v36, v37
	v_cvt_pk_bf16_f32 v37, v38, v39
	v_cvt_pk_bf16_f32 v38, v32, v33
	v_cvt_pk_bf16_f32 v39, v34, v35
	v_add_u32_e32 v140, 0xc6000, v139
	global_store_dwordx4 v140, v[44:47], s[8:9] sc1
	v_add_u32_e32 v141, 0xc6100, v139
	global_store_dwordx4 v141, v[36:39], s[8:9] sc1
	v_pk_mul_f32 v[28:29], v[28:29], v[214:215] op_sel_hi:[1,0]
	v_pk_mul_f32 v[30:31], v[30:31], v[214:215] op_sel_hi:[1,0]
	v_pk_mul_f32 v[24:25], v[24:25], v[214:215] op_sel_hi:[1,0]
	v_pk_mul_f32 v[26:27], v[26:27], v[214:215] op_sel_hi:[1,0]
	v_pk_mul_f32 v[20:21], v[20:21], v[214:215] op_sel_hi:[1,0]
	v_pk_mul_f32 v[22:23], v[22:23], v[214:215] op_sel_hi:[1,0]
	v_pk_mul_f32 v[16:17], v[16:17], v[214:215] op_sel_hi:[1,0]
	v_pk_mul_f32 v[18:19], v[18:19], v[214:215] op_sel_hi:[1,0]
	v_pk_mul_f32 v[218:219], v[28:29], v[134:135] op_sel_hi:[1,0]
	v_pk_mul_f32 v[220:221], v[30:31], v[134:135] op_sel_hi:[1,0]
	v_pk_mul_f32 v[222:223], v[24:25], v[134:135] op_sel_hi:[1,0]
	v_pk_mul_f32 v[224:225], v[26:27], v[134:135] op_sel_hi:[1,0]
	v_pk_mul_f32 v[226:227], v[20:21], v[134:135] op_sel_hi:[1,0]
	v_pk_mul_f32 v[228:229], v[22:23], v[134:135] op_sel_hi:[1,0]
	v_pk_mul_f32 v[230:231], v[16:17], v[134:135] op_sel_hi:[1,0]
	v_pk_mul_f32 v[232:233], v[18:19], v[134:135] op_sel_hi:[1,0]
	v_pk_mul_f32 v[218:219], v[28:29], v[218:219]
	v_pk_mul_f32 v[220:221], v[30:31], v[220:221]
	v_pk_mul_f32 v[222:223], v[24:25], v[222:223]
	v_pk_mul_f32 v[224:225], v[26:27], v[224:225]
	v_pk_mul_f32 v[226:227], v[20:21], v[226:227]
	v_pk_mul_f32 v[228:229], v[22:23], v[228:229]
	v_pk_mul_f32 v[230:231], v[16:17], v[230:231]
	v_pk_mul_f32 v[232:233], v[18:19], v[232:233]
	v_pk_fma_f32 v[218:219], v[28:29], v[218:219], v[28:29]
	v_pk_fma_f32 v[220:221], v[30:31], v[220:221], v[30:31]
	v_pk_fma_f32 v[222:223], v[24:25], v[222:223], v[24:25]
	v_pk_fma_f32 v[224:225], v[26:27], v[224:225], v[26:27]
	v_pk_fma_f32 v[226:227], v[20:21], v[226:227], v[20:21]
	v_pk_fma_f32 v[228:229], v[22:23], v[228:229], v[22:23]
	v_pk_fma_f32 v[230:231], v[16:17], v[230:231], v[16:17]
	v_pk_fma_f32 v[232:233], v[18:19], v[232:233], v[18:19]
	v_pk_mul_f32 v[218:219], v[218:219], v[136:137] op_sel_hi:[1,0]
	v_pk_mul_f32 v[220:221], v[220:221], v[136:137] op_sel_hi:[1,0]
	v_pk_mul_f32 v[222:223], v[222:223], v[136:137] op_sel_hi:[1,0]
	v_pk_mul_f32 v[224:225], v[224:225], v[136:137] op_sel_hi:[1,0]
	v_pk_mul_f32 v[226:227], v[226:227], v[136:137] op_sel_hi:[1,0]
	v_pk_mul_f32 v[228:229], v[228:229], v[136:137] op_sel_hi:[1,0]
	v_pk_mul_f32 v[230:231], v[230:231], v[136:137] op_sel_hi:[1,0]
	v_pk_mul_f32 v[232:233], v[232:233], v[136:137] op_sel_hi:[1,0]
	v_pk_mul_f32 v[218:219], v[218:219], v[132:133] op_sel_hi:[1,0]
	v_pk_mul_f32 v[220:221], v[220:221], v[132:133] op_sel_hi:[1,0]
	v_pk_mul_f32 v[222:223], v[222:223], v[132:133] op_sel_hi:[1,0]
	v_pk_mul_f32 v[224:225], v[224:225], v[132:133] op_sel_hi:[1,0]
; __device__ __forceinline__ unsigned pk2(float lo, float hi) { return pg8::cvt_pk_bf16(lo, hi); }
; __device__ __forceinline__ float siluf_(float x) { return x * sigmoidf_(x); }
; __device__ __forceinline__ float geluf_(float x) { const float z = 1.5957691216057308f * (x + 0.044715f * x * x * x); return x * sigmoidf_(z); }
;     __device__ __forceinline__ void operator()(const f32x4 (&acc)[2][2][4][2], const pg8::Unit& u, int wr, int wc, int fr, int fq) const {
;     ...
;             const int act = (pn == 7 || pn == 8) ? 1 : (pn == 10 ? 2 : 0);
; #pragma unroll
;             for (int ai = 0; ai < 2; ++ai)
; #pragma unroll
;                 for (int m = 0; m < 4; ++m) {
;                     const int row = row0 + ai * 128 + m * 16; const float r = rs[ai * 4 + m];
; #pragma unroll
;                     for (int bj = 0; bj < 2; ++bj) {
;                         float v[8];
; #pragma unroll
;                         for (int n = 0; n < 2; ++n)
; #pragma unroll
;                             for (int j = 0; j < 4; ++j) { float t = acc[ai][bj][m][n][j] * r; if (act == 1) t = siluf_(t); else if (act == 2) t = geluf_(t); v[n * 4 + j] = t; }
;                         u32x4 w; w.x = pk2(v[0], v[1]); w.y = pk2(v[2], v[3]); w.z = pk2(v[4], v[5]); w.w = pk2(v[6], v[7]);
;                         *(u32x4*)(Z + (size_t)row * IW + pn * 256 + bj * 128 + wc * 32 + 8 * fq) = w;
;                     }
;                 }
	v_pk_mul_f32 v[226:227], v[226:227], v[132:133] op_sel_hi:[1,0]
	v_pk_mul_f32 v[228:229], v[228:229], v[132:133] op_sel_hi:[1,0]
	v_pk_mul_f32 v[230:231], v[230:231], v[132:133] op_sel_hi:[1,0]
	v_pk_mul_f32 v[232:233], v[232:233], v[132:133] op_sel_hi:[1,0]
	v_exp_f32_e32 v218, v218
	v_exp_f32_e32 v219, v219
	v_exp_f32_e32 v220, v220
	v_exp_f32_e32 v221, v221
	v_exp_f32_e32 v222, v222
	v_exp_f32_e32 v223, v223
	v_exp_f32_e32 v224, v224
	v_exp_f32_e32 v225, v225
	v_exp_f32_e32 v226, v226
	v_exp_f32_e32 v227, v227
	v_exp_f32_e32 v228, v228
	v_exp_f32_e32 v229, v229
	v_exp_f32_e32 v230, v230
	v_exp_f32_e32 v231, v231
	v_exp_f32_e32 v232, v232
	v_exp_f32_e32 v233, v233
	v_pk_add_f32 v[218:219], v[218:219], v[128:129]
	v_pk_add_f32 v[220:221], v[220:221], v[128:129]
	v_pk_add_f32 v[222:223], v[222:223], v[128:129]
	v_pk_add_f32 v[224:225], v[224:225], v[128:129]
	v_pk_add_f32 v[226:227], v[226:227], v[128:129]
	v_pk_add_f32 v[228:229], v[228:229], v[128:129]
	v_pk_add_f32 v[230:231], v[230:231], v[128:129]
	v_pk_add_f32 v[232:233], v[232:233], v[128:129]
	v_rcp_f32_e32 v218, v218
	v_rcp_f32_e32 v219, v219
	v_rcp_f32_e32 v220, v220
	v_rcp_f32_e32 v221, v221
	v_rcp_f32_e32 v222, v222
	v_rcp_f32_e32 v223, v223
	v_rcp_f32_e32 v224, v224
	v_rcp_f32_e32 v225, v225
	v_rcp_f32_e32 v226, v226
	v_rcp_f32_e32 v227, v227
	v_rcp_f32_e32 v228, v228
	v_rcp_f32_e32 v229, v229
	v_rcp_f32_e32 v230, v230
	v_rcp_f32_e32 v231, v231
	v_rcp_f32_e32 v232, v232
	v_rcp_f32_e32 v233, v233
	v_pk_mul_f32 v[28:29], v[28:29], v[218:219]
	v_pk_mul_f32 v[30:31], v[30:31], v[220:221]
	v_pk_mul_f32 v[24:25], v[24:25], v[222:223]
	v_pk_mul_f32 v[26:27], v[26:27], v[224:225]
	v_pk_mul_f32 v[20:21], v[20:21], v[226:227]
	v_pk_mul_f32 v[22:23], v[22:23], v[228:229]
	v_pk_mul_f32 v[16:17], v[16:17], v[230:231]
	v_pk_mul_f32 v[18:19], v[18:19], v[232:233]
	v_cvt_pk_bf16_f32 v28, v28, v29
	v_cvt_pk_bf16_f32 v29, v30, v31
	v_cvt_pk_bf16_f32 v30, v24, v25
	v_cvt_pk_bf16_f32 v31, v26, v27
	v_cvt_pk_bf16_f32 v20, v20, v21
	v_cvt_pk_bf16_f32 v21, v22, v23
	v_cvt_pk_bf16_f32 v22, v16, v17
	v_cvt_pk_bf16_f32 v23, v18, v19
	v_add_u32_e32 v140, 0xdc000, v139
	global_store_dwordx4 v140, v[28:31], s[8:9] sc1
	v_add_u32_e32 v141, 0xdc100, v139
	global_store_dwordx4 v141, v[20:23], s[8:9] sc1
	v_pk_mul_f32 v[12:13], v[12:13], v[216:217] op_sel_hi:[1,0]
	v_pk_mul_f32 v[14:15], v[14:15], v[216:217] op_sel_hi:[1,0]
	v_pk_mul_f32 v[8:9], v[8:9], v[216:217] op_sel_hi:[1,0]
	v_pk_mul_f32 v[10:11], v[10:11], v[216:217] op_sel_hi:[1,0]
	v_pk_mul_f32 v[4:5], v[4:5], v[216:217] op_sel_hi:[1,0]
	v_pk_mul_f32 v[6:7], v[6:7], v[216:217] op_sel_hi:[1,0]
	v_pk_mul_f32 v[0:1], v[0:1], v[216:217] op_sel_hi:[1,0]
	v_pk_mul_f32 v[2:3], v[2:3], v[216:217] op_sel_hi:[1,0]
	v_pk_mul_f32 v[218:219], v[12:13], v[134:135] op_sel_hi:[1,0]
	v_pk_mul_f32 v[220:221], v[14:15], v[134:135] op_sel_hi:[1,0]
	v_pk_mul_f32 v[222:223], v[8:9], v[134:135] op_sel_hi:[1,0]
	v_pk_mul_f32 v[224:225], v[10:11], v[134:135] op_sel_hi:[1,0]
	v_pk_mul_f32 v[226:227], v[4:5], v[134:135] op_sel_hi:[1,0]
	v_pk_mul_f32 v[228:229], v[6:7], v[134:135] op_sel_hi:[1,0]
	v_pk_mul_f32 v[230:231], v[0:1], v[134:135] op_sel_hi:[1,0]
	v_pk_mul_f32 v[232:233], v[2:3], v[134:135] op_sel_hi:[1,0]
	v_pk_mul_f32 v[218:219], v[12:13], v[218:219]
	v_pk_mul_f32 v[220:221], v[14:15], v[220:221]
	v_pk_mul_f32 v[222:223], v[8:9], v[222:223]
	v_pk_mul_f32 v[224:225], v[10:11], v[224:225]
	v_pk_mul_f32 v[226:227], v[4:5], v[226:227]
	v_pk_mul_f32 v[228:229], v[6:7], v[228:229]
	v_pk_mul_f32 v[230:231], v[0:1], v[230:231]
; __device__ __forceinline__ unsigned pk2(float lo, float hi) { return pg8::cvt_pk_bf16(lo, hi); }
; __device__ __forceinline__ float siluf_(float x) { return x * sigmoidf_(x); }
; __device__ __forceinline__ float geluf_(float x) { const float z = 1.5957691216057308f * (x + 0.044715f * x * x * x); return x * sigmoidf_(z); }
;     __device__ __forceinline__ void operator()(const f32x4 (&acc)[2][2][4][2], const pg8::Unit& u, int wr, int wc, int fr, int fq) const {
;     ...
;             const int act = (pn == 7 || pn == 8) ? 1 : (pn == 10 ? 2 : 0);
; #pragma unroll
;             for (int ai = 0; ai < 2; ++ai)
; #pragma unroll
;                 for (int m = 0; m < 4; ++m) {
;                     const int row = row0 + ai * 128 + m * 16; const float r = rs[ai * 4 + m];
; #pragma unroll
;                     for (int bj = 0; bj < 2; ++bj) {
;                         float v[8];
; #pragma unroll
;                         for (int n = 0; n < 2; ++n)
; #pragma unroll
;                             for (int j = 0; j < 4; ++j) { float t = acc[ai][bj][m][n][j] * r; if (act == 1) t = siluf_(t); else if (act == 2) t = geluf_(t); v[n * 4 + j] = t; }
;                         u32x4 w; w.x = pk2(v[0], v[1]); w.y = pk2(v[2], v[3]); w.z = pk2(v[4], v[5]); w.w = pk2(v[6], v[7]);
;                         *(u32x4*)(Z + (size_t)row * IW + pn * 256 + bj * 128 + wc * 32 + 8 * fq) = w;
;                     }
;                 }
	v_pk_mul_f32 v[232:233], v[2:3], v[232:233]
	v_pk_fma_f32 v[218:219], v[12:13], v[218:219], v[12:13]
	v_pk_fma_f32 v[220:221], v[14:15], v[220:221], v[14:15]
	v_pk_fma_f32 v[222:223], v[8:9], v[222:223], v[8:9]
	v_pk_fma_f32 v[224:225], v[10:11], v[224:225], v[10:11]
	v_pk_fma_f32 v[226:227], v[4:5], v[226:227], v[4:5]
	v_pk_fma_f32 v[228:229], v[6:7], v[228:229], v[6:7]
	v_pk_fma_f32 v[230:231], v[0:1], v[230:231], v[0:1]
	v_pk_fma_f32 v[232:233], v[2:3], v[232:233], v[2:3]
	v_pk_mul_f32 v[218:219], v[218:219], v[136:137] op_sel_hi:[1,0]
	v_pk_mul_f32 v[220:221], v[220:221], v[136:137] op_sel_hi:[1,0]
	v_pk_mul_f32 v[222:223], v[222:223], v[136:137] op_sel_hi:[1,0]
	v_pk_mul_f32 v[224:225], v[224:225], v[136:137] op_sel_hi:[1,0]
	v_pk_mul_f32 v[226:227], v[226:227], v[136:137] op_sel_hi:[1,0]
	v_pk_mul_f32 v[228:229], v[228:229], v[136:137] op_sel_hi:[1,0]
	v_pk_mul_f32 v[230:231], v[230:231], v[136:137] op_sel_hi:[1,0]
	v_pk_mul_f32 v[232:233], v[232:233], v[136:137] op_sel_hi:[1,0]
	v_pk_mul_f32 v[218:219], v[218:219], v[132:133] op_sel_hi:[1,0]
	v_pk_mul_f32 v[220:221], v[220:221], v[132:133] op_sel_hi:[1,0]
	v_pk_mul_f32 v[222:223], v[222:223], v[132:133] op_sel_hi:[1,0]
	v_pk_mul_f32 v[224:225], v[224:225], v[132:133] op_sel_hi:[1,0]
	v_pk_mul_f32 v[226:227], v[226:227], v[132:133] op_sel_hi:[1,0]
	v_pk_mul_f32 v[228:229], v[228:229], v[132:133] op_sel_hi:[1,0]
	v_pk_mul_f32 v[230:231], v[230:231], v[132:133] op_sel_hi:[1,0]
	v_pk_mul_f32 v[232:233], v[232:233], v[132:133] op_sel_hi:[1,0]
	v_exp_f32_e32 v218, v218
	v_exp_f32_e32 v219, v219
	v_exp_f32_e32 v220, v220
	v_exp_f32_e32 v221, v221
	v_exp_f32_e32 v222, v222
	v_exp_f32_e32 v223, v223
	v_exp_f32_e32 v224, v224
	v_exp_f32_e32 v225, v225
	v_exp_f32_e32 v226, v226
	v_exp_f32_e32 v227, v227
	v_exp_f32_e32 v228, v228
	v_exp_f32_e32 v229, v229
	v_exp_f32_e32 v230, v230
	v_exp_f32_e32 v231, v231
	v_exp_f32_e32 v232, v232
	v_exp_f32_e32 v233, v233
	v_pk_add_f32 v[218:219], v[218:219], v[128:129]
	v_pk_add_f32 v[220:221], v[220:221], v[128:129]
	v_pk_add_f32 v[222:223], v[222:223], v[128:129]
	v_pk_add_f32 v[224:225], v[224:225], v[128:129]
	v_pk_add_f32 v[226:227], v[226:227], v[128:129]
	v_pk_add_f32 v[228:229], v[228:229], v[128:129]
	v_pk_add_f32 v[230:231], v[230:231], v[128:129]
	v_pk_add_f32 v[232:233], v[232:233], v[128:129]
	v_rcp_f32_e32 v218, v218
	v_rcp_f32_e32 v219, v219
	v_rcp_f32_e32 v220, v220
	v_rcp_f32_e32 v221, v221
	v_rcp_f32_e32 v222, v222
	v_rcp_f32_e32 v223, v223
	v_rcp_f32_e32 v224, v224
	v_rcp_f32_e32 v225, v225
	v_rcp_f32_e32 v226, v226
	v_rcp_f32_e32 v227, v227
	v_rcp_f32_e32 v228, v228
	v_rcp_f32_e32 v229, v229
	v_rcp_f32_e32 v230, v230
	v_rcp_f32_e32 v231, v231
	v_rcp_f32_e32 v232, v232
	v_rcp_f32_e32 v233, v233
	v_pk_mul_f32 v[12:13], v[12:13], v[218:219]
	v_pk_mul_f32 v[14:15], v[14:15], v[220:221]
	v_pk_mul_f32 v[8:9], v[8:9], v[222:223]
	v_pk_mul_f32 v[10:11], v[10:11], v[224:225]
	v_pk_mul_f32 v[4:5], v[4:5], v[226:227]
	v_pk_mul_f32 v[6:7], v[6:7], v[228:229]
	v_pk_mul_f32 v[0:1], v[0:1], v[230:231]
	v_pk_mul_f32 v[2:3], v[2:3], v[232:233]
	v_cvt_pk_bf16_f32 v12, v12, v13
	v_cvt_pk_bf16_f32 v13, v14, v15
	v_cvt_pk_bf16_f32 v14, v8, v9
	v_cvt_pk_bf16_f32 v15, v10, v11
	v_cvt_pk_bf16_f32 v4, v4, v5
	v_cvt_pk_bf16_f32 v5, v6, v7
	v_cvt_pk_bf16_f32 v6, v0, v1
	v_cvt_pk_bf16_f32 v7, v2, v3
	v_add_u32_e32 v140, 0xf2000, v139
	global_store_dwordx4 v140, v[12:15], s[8:9] sc1
	v_add_u32_e32 v141, 0xf2100, v139
	global_store_dwordx4 v141, v[4:7], s[8:9] sc1
	s_branch .LBB0_1021
